# RG-LRU: all 16 B fragments of the next gate cluster read right after the carry composition into free conv staging registers; cluster = single wait + 18 back-to-back MFMAs
# baseline (speedup 1.0000x reference)
.LBB0_270:
	ds_read_b128 v[178:181], v145 offset:24576
	ds_read_b128 v[182:185], v145 offset:57344
	ds_read_b128 v[186:189], v147 offset:24576
	ds_read_b128 v[190:193], v147 offset:57344
	ds_read_b128 v[194:197], v142 offset:24576
	ds_read_b128 v[198:201], v142 offset:57344
	ds_read_b128 v[202:205], v146 offset:24576
	ds_read_b128 v[206:209], v146 offset:57344
	ds_read_b128 v[210:213], v141 offset:24576
	ds_read_b128 v[214:217], v141 offset:57344
	ds_read_b128 v[218:221], v144 offset:24576
	ds_read_b128 v[222:225], v144 offset:57344
	ds_read_b128 v[226:229], v139 offset:24576
	ds_read_b128 v[230:233], v139 offset:57344
	ds_read_b128 v[234:237], v143 offset:24576
	ds_read_b128 v[238:241], v143 offset:57344
	v_cndmask_b32_e64 v0, 1.0, v35, s[4:5]
	v_cndmask_b32_e64 v35, 0, v37, s[4:5]
	v_cndmask_b32_e64 v37, v38, v41, s[4:5]
	v_cndmask_b32_e64 v36, v36, v40, s[4:5]
	v_cndmask_b32_e64 v40, v46, v88, s[4:5]
	v_cndmask_b32_e64 v41, v43, v47, s[4:5]
	s_ashr_i32 s13, s12, 31
	v_lshlrev_b32_e32 v88, 2, v93
	v_fmac_f32_e32 v25, v32, v41
	v_mul_f32_e32 v32, v32, v40
	v_fmac_f32_e32 v9, v34, v36
	v_mul_f32_e32 v34, v34, v37
	v_fmac_f32_e32 v10, v31, v36
	v_mul_f32_e32 v31, v31, v37
	v_fmac_f32_e32 v5, v28, v36
	v_mul_f32_e32 v28, v28, v37
	v_fmac_f32_e32 v11, v18, v36
	v_mul_f32_e32 v18, v18, v37
	v_fmac_f32_e32 v6, v12, v35
	v_mul_f32_e32 v36, v0, v12
	v_fmac_f32_e32 v4, v13, v35
	v_mul_f32_e32 v37, v0, v13
	v_lshl_add_u64 v[12:13], s[24:25], 0, v[88:89]
	s_lshl_b64 s[6:7], s[12:13], 12
	v_lshl_add_u64 v[94:95], v[12:13], 0, s[6:7]
	v_mul_f32_e32 v13, v32, v8
	v_fmac_f32_e32 v23, v29, v41
	v_mul_f32_e32 v29, v29, v40
	v_fmac_f32_e32 v21, v26, v41
	v_mul_f32_e32 v26, v26, v40
	v_fmac_f32_e32 v3, v16, v41
	v_mul_f32_e32 v40, v16, v40
	v_lshlrev_b32_e32 v12, 14, v92
	v_fmac_f32_e32 v25, v32, v1
	v_cvt_pk_bf16_f32 v16, v25, v13
	v_mov_b32_e32 v13, v89
	v_cndmask_b32_e64 v38, v42, v45, s[4:5]
	v_cndmask_b32_e64 v39, v39, v44, s[4:5]
	v_lshl_add_u64 v[96:97], v[94:95], 0, v[12:13]
	v_mul_f32_e32 v13, v29, v8
	v_or_b32_e32 v88, 0x1000, v12
	v_fmac_f32_e32 v22, v33, v39
	v_mul_f32_e32 v33, v33, v38
	v_fmac_f32_e32 v20, v30, v39
	v_mul_f32_e32 v30, v30, v38
	v_fmac_f32_e32 v19, v27, v39
	v_mul_f32_e32 v27, v27, v38
	v_fmac_f32_e32 v7, v17, v39
	v_mul_f32_e32 v38, v17, v38
	v_lshl_or_b32 v175, v138, 2, v133
	global_load_dword v172, v175, s[42:43]
	global_load_dword v173, v175, s[36:37]
	global_load_dword v174, v175, s[40:41]
	global_store_dword v[96:97], v16, off nt
	v_fmac_f32_e32 v23, v29, v1
	v_cvt_pk_bf16_f32 v13, v23, v13
	v_lshl_add_u64 v[16:17], v[94:95], 0, v[88:89]
	global_store_dword v[16:17], v13, off nt
	v_mul_f32_e32 v13, v26, v8
	v_or_b32_e32 v98, 0x2000, v12
	v_mov_b32_e32 v99, v89
	v_fmac_f32_e32 v21, v26, v1
	v_cvt_pk_bf16_f32 v13, v21, v13
	v_lshl_add_u64 v[16:17], v[94:95], 0, v[98:99]
	v_fmac_f32_e32 v3, v40, v1
	v_or_b32_e32 v100, 0x3000, v12
	v_mov_b32_e32 v101, v89
	global_store_dword v[16:17], v13, off nt
	v_mul_f32_e32 v13, v40, v8
	v_cvt_pk_bf16_f32 v3, v3, v13
	v_lshl_add_u64 v[16:17], v[94:95], 0, v[100:101]
	global_store_dword v[16:17], v3, off nt
	v_mul_f32_e32 v3, v33, v8
	v_or_b32_e32 v102, 0x8000, v12
	v_mov_b32_e32 v103, v89
	v_fmac_f32_e32 v22, v33, v1
	v_cvt_pk_bf16_f32 v3, v22, v3
	v_lshl_add_u64 v[16:17], v[94:95], 0, v[102:103]
	global_store_dword v[16:17], v3, off nt
	v_mul_f32_e32 v3, v30, v8
	v_or_b32_e32 v104, 0x9000, v12
	v_mov_b32_e32 v105, v89
	v_fmac_f32_e32 v20, v30, v1
	v_cvt_pk_bf16_f32 v3, v20, v3
	v_lshl_add_u64 v[16:17], v[94:95], 0, v[104:105]
	global_store_dword v[16:17], v3, off nt
	v_mul_f32_e32 v3, v27, v8
	v_or_b32_e32 v106, 0xa000, v12
	v_mov_b32_e32 v107, v89
	v_fmac_f32_e32 v19, v27, v1
	v_cvt_pk_bf16_f32 v3, v19, v3
	v_lshl_add_u64 v[16:17], v[94:95], 0, v[106:107]
	global_store_dword v[16:17], v3, off nt
	v_mul_f32_e32 v3, v38, v8
	v_or_b32_e32 v108, 0xb000, v12
	v_mov_b32_e32 v109, v89
	v_fmac_f32_e32 v7, v38, v1
	v_cvt_pk_bf16_f32 v3, v7, v3
	v_lshl_add_u64 v[16:17], v[94:95], 0, v[108:109]
	global_store_dword v[16:17], v3, off nt
	v_mul_f32_e32 v3, v34, v8
	v_or_b32_e32 v110, 0x10000, v12
	v_mov_b32_e32 v111, v89
	v_fmac_f32_e32 v9, v34, v1
	v_cvt_pk_bf16_f32 v3, v9, v3
	v_lshl_add_u64 v[16:17], v[94:95], 0, v[110:111]
	global_store_dword v[16:17], v3, off nt
	v_mul_f32_e32 v3, v31, v8
	v_or_b32_e32 v112, 0x11000, v12
	v_mov_b32_e32 v113, v89
	v_fmac_f32_e32 v10, v31, v1
	v_cvt_pk_bf16_f32 v3, v10, v3
	v_lshl_add_u64 v[16:17], v[94:95], 0, v[112:113]
	global_store_dword v[16:17], v3, off nt
	v_mul_f32_e32 v3, v28, v8
	v_or_b32_e32 v114, 0x12000, v12
	v_mov_b32_e32 v115, v89
	v_fmac_f32_e32 v5, v28, v1
	v_cvt_pk_bf16_f32 v3, v5, v3
	v_lshl_add_u64 v[16:17], v[94:95], 0, v[114:115]
	global_store_dword v[16:17], v3, off nt
	v_fmac_f32_e32 v11, v18, v1
	v_mul_f32_e32 v3, v18, v8
	v_or_b32_e32 v116, 0x13000, v12
	v_mov_b32_e32 v117, v89
	v_cvt_pk_bf16_f32 v3, v11, v3
	v_lshl_add_u64 v[10:11], v[94:95], 0, v[116:117]
	global_store_dword v[10:11], v3, off nt
	v_fmac_f32_e32 v6, v36, v1
	v_mul_f32_e32 v3, v36, v8
	v_or_b32_e32 v118, 0x18000, v12
	v_mov_b32_e32 v119, v89
	v_cvt_pk_bf16_f32 v3, v6, v3
	v_lshl_add_u64 v[6:7], v[94:95], 0, v[118:119]
	global_store_dword v[6:7], v3, off nt
	v_fmac_f32_e32 v4, v37, v1
	v_mul_f32_e32 v3, v37, v8
	v_or_b32_e32 v120, 0x19000, v12
	v_mov_b32_e32 v121, v89
	v_fmac_f32_e32 v2, v14, v35
	v_mul_f32_e32 v14, v0, v14
	v_cvt_pk_bf16_f32 v3, v4, v3
	v_lshl_add_u64 v[4:5], v[94:95], 0, v[120:121]
	v_fmac_f32_e32 v15, v24, v35
	v_mul_f32_e32 v0, v0, v24
	s_lshl_b32 s8, s65, 11
	global_store_dword v[4:5], v3, off nt
	v_fmac_f32_e32 v2, v14, v1
	v_mul_f32_e32 v3, v14, v8
	v_or_b32_e32 v122, 0x1a000, v12
	v_mov_b32_e32 v123, v89
	s_or_b32 s8, s8, s76
	v_cvt_pk_bf16_f32 v4, v2, v3
	v_lshl_add_u64 v[2:3], v[94:95], 0, v[122:123]
	v_fmac_f32_e32 v15, v0, v1
	v_mul_f32_e32 v0, v0, v8
	v_or_b32_e32 v124, 0x1b000, v12
	v_mov_b32_e32 v125, v89
	v_cmp_gt_i32_e64 s[6:7], 32, v90
	v_add_u32_e32 v92, s8, v90
	global_store_dword v[2:3], v4, off nt
	v_cvt_pk_bf16_f32 v2, v15, v0
	v_lshl_add_u64 v[0:1], v[94:95], 0, v[124:125]
	v_lshl_add_u32 v90, v90, 3, 16
	global_store_dword v[0:1], v2, off nt
	s_and_saveexec_b64 s[8:9], s[6:7]
	s_cbranch_execz .LBB0_272
	ds_read2_b64 v[0:3], v90 offset0:192 offset1:224
	ds_read2_b64 v[4:7], v90 offset0:128 offset1:160
	ds_read2_b64 v[8:11], v90 offset0:64 offset1:96
	ds_read2_b64 v[12:15], v90 offset1:32
	v_ashrrev_i32_e32 v93, 31, v92
	s_waitcnt lgkmcnt(3)
	v_fma_f32 v16, 0, v2, v3
	v_pk_mul_f32 v[2:3], v[2:3], v[0:1]
	v_fma_f32 v0, v0, v16, v1
	s_waitcnt lgkmcnt(2)
	v_fma_f32 v0, v6, v0, v7
	v_fma_f32 v0, v4, v0, v5
	s_waitcnt lgkmcnt(1)
	v_fma_f32 v1, v10, v0, v11
	v_mov_b32_e32 v0, v2
	v_mov_b32_e32 v16, v6
	v_mov_b32_e32 v17, v8
	v_pk_mul_f32 v[2:3], v[2:3], v[6:7]
	v_pk_fma_f32 v[0:1], v[0:1], v[16:17], v[8:9]
	v_pk_mul_f32 v[2:3], v[2:3], v[4:5]
	s_waitcnt lgkmcnt(0)
	v_mov_b32_e32 v11, v14
	v_mov_b32_e32 v3, v1
	v_pk_mul_f32 v[0:1], v[2:3], v[10:11]
	v_pk_fma_f32 v[2:3], v[2:3], v[10:11], v[14:15]
	v_pk_mul_f32 v[0:1], v[0:1], v[8:9]
	v_mov_b32_e32 v4, v14
	v_mov_b32_e32 v2, v0
	v_mov_b32_e32 v5, v12
	v_pk_mul_f32 v[0:1], v[0:1], v[14:15]
	v_pk_fma_f32 v[2:3], v[2:3], v[4:5], v[12:13]
	v_pk_mul_f32 v[0:1], v[0:1], v[12:13]
	s_nop 0
	v_mov_b32_e32 v1, v3
	v_lshl_add_u64 v[2:3], v[92:93], 3, s[30:31]
	global_store_dwordx2 v[2:3], v[0:1], off
.LBB0_272:
	s_or_b64 exec, exec, s[8:9]
	s_setprio 1
	s_waitcnt lgkmcnt(0)
	v_mfma_f32_32x32x16_bf16 v[32:47], v[48:51], v[178:181], 0
	v_mfma_f32_32x32x16_bf16 v[16:31], v[48:51], v[182:185], 0
	v_mfma_f32_32x32x16_bf16 v[32:47], v[52:55], v[186:189], v[32:47]
	v_mfma_f32_32x32x16_bf16 v[16:31], v[52:55], v[190:193], v[16:31]
	v_mfma_f32_32x32x16_bf16 v[32:47], v[56:59], v[194:197], v[32:47]
	v_mfma_f32_32x32x16_bf16 v[16:31], v[56:59], v[198:201], v[16:31]
	v_mfma_f32_32x32x16_bf16 v[32:47], v[60:63], v[202:205], v[32:47]
	v_mfma_f32_32x32x16_bf16 v[16:31], v[60:63], v[206:209], v[16:31]
	v_mfma_f32_32x32x16_bf16 v[32:47], v[64:67], v[210:213], v[32:47]
	v_mfma_f32_32x32x16_bf16 v[16:31], v[64:67], v[214:217], v[16:31]
	v_mfma_f32_32x32x16_bf16 v[32:47], v[68:71], v[218:221], v[32:47]
	v_mfma_f32_32x32x16_bf16 v[16:31], v[68:71], v[222:225], v[16:31]
	v_mfma_f32_32x32x16_bf16 v[32:47], v[72:75], v[226:229], v[32:47]
	v_mfma_f32_32x32x16_bf16 v[16:31], v[72:75], v[230:233], v[16:31]
	v_mfma_f32_32x32x16_bf16 v[32:47], v[76:79], v[234:237], v[32:47]
	v_mfma_f32_32x32x16_bf16 v[16:31], v[76:79], v[238:241], v[16:31]
	v_mfma_f32_32x32x16_bf16 v[0:15], v[56:59], v[80:83], 0
	v_mfma_f32_32x32x16_bf16 v[0:15], v[60:63], v[84:87], v[0:15]
	s_setprio 0
	v_lshl_or_b32 v93, v138, 2, v133
	s_waitcnt vmcnt(16)
	ds_read_b32 v251, v167 offset:128
	v_mul_f32_e32 v148, 0xbfb8aa3b, v173
	v_mul_f32_e32 v93, 0xbfb8aa3b, v174
	v_fmamk_f32 v32, v32, 0xbfb8aa3b, v148
	v_fmamk_f32 v16, v16, 0xbfb8aa3b, v93
	v_exp_f32_e32 v32, v32
	v_exp_f32_e32 v150, v16
	v_fmamk_f32 v17, v17, 0xbfb8aa3b, v93
	v_exp_f32_e32 v151, v17
	v_add_f32_e32 v32, 1.0, v32
	v_add_f32_e32 v150, 1.0, v150
	v_rcp_f32_e32 v17, v32
	v_rcp_f32_e32 v32, v150
	v_fmamk_f32 v33, v33, 0xbfb8aa3b, v148
	v_fmamk_f32 v34, v34, 0xbfb8aa3b, v148
	v_exp_f32_e32 v33, v33
	v_exp_f32_e32 v34, v34
	v_add_f32_e32 v33, 1.0, v33
	v_add_f32_e32 v34, 1.0, v34
	v_rcp_f32_e32 v33, v33
	v_rcp_f32_e32 v34, v34
	v_fmamk_f32 v18, v18, 0xbfb8aa3b, v93
	v_fmamk_f32 v19, v19, 0xbfb8aa3b, v93
	v_exp_f32_e32 v18, v18
	s_waitcnt lgkmcnt(0)
	v_mul_f32_e32 v149, 0x3fb8aa3b, v251
	v_mul_f32_e32 v16, v17, v149
	v_mul_f32_e32 v17, v33, v149
	v_exp_f32_e32 v33, v16
	v_mul_f32_e32 v16, v34, v149
	v_exp_f32_e32 v152, v16
	v_fmamk_f32 v16, v35, 0xbfb8aa3b, v148
	v_exp_f32_e32 v16, v16
	v_exp_f32_e32 v150, v17
	v_add_f32_e32 v16, 1.0, v16
	v_rcp_f32_e32 v16, v16
	v_exp_f32_e32 v19, v19
	v_add_f32_e32 v151, 1.0, v151
	v_add_f32_e32 v18, 1.0, v18
	v_mul_f32_e32 v16, v16, v149
	v_exp_f32_e32 v16, v16
	v_fma_f32 v35, -v152, v152, 1.0
	v_rcp_f32_e32 v17, v151
	v_fma_f32 v34, -v33, v33, 1.0
	v_fma_f32 v151, -v150, v150, 1.0
	v_rcp_f32_e32 v18, v18
	v_sqrt_f32_e32 v35, v35
	v_add_f32_e32 v19, 1.0, v19
	v_fma_f32 v153, -v16, v16, 1.0
	v_sqrt_f32_e32 v34, v34
	v_sqrt_f32_e32 v151, v151
	v_rcp_f32_e32 v19, v19
	v_sqrt_f32_e32 v153, v153
	v_mul_f32_e32 v35, v18, v35
	v_fmamk_f32 v18, v36, 0xbfb8aa3b, v148
	v_mul_f32_e32 v32, v32, v34
	v_mul_f32_e32 v34, v17, v151
	v_mul_f32_e32 v17, v19, v153
	v_fmamk_f32 v19, v20, 0xbfb8aa3b, v93
	v_exp_f32_e32 v18, v18
	v_exp_f32_e32 v19, v19
	v_mul_f32_e32 v3, v3, v17
	v_add_f32_e32 v17, 1.0, v18
	v_rcp_f32_e32 v17, v17
	v_add_f32_e32 v18, 1.0, v19
	v_fmamk_f32 v19, v37, 0xbfb8aa3b, v148
	v_exp_f32_e32 v19, v19
	v_mul_f32_e32 v17, v17, v149
	v_exp_f32_e32 v36, v17
	v_add_f32_e32 v17, 1.0, v19
	v_rcp_f32_e32 v17, v17
	v_fmamk_f32 v19, v21, 0xbfb8aa3b, v93
	v_exp_f32_e32 v19, v19
	v_mul_f32_e32 v17, v17, v149
	v_exp_f32_e32 v37, v17
	v_fmamk_f32 v17, v38, 0xbfb8aa3b, v148
	v_exp_f32_e32 v17, v17
	v_fmamk_f32 v23, v23, 0xbfb8aa3b, v93
	v_add_f32_e32 v19, 1.0, v19
	v_fma_f32 v21, -v37, v37, 1.0
	v_add_f32_e32 v17, 1.0, v17
	v_rcp_f32_e32 v17, v17
	v_fma_f32 v20, -v36, v36, 1.0
	v_rcp_f32_e32 v19, v19
	v_mul_f32_e32 v17, v17, v149
	v_exp_f32_e32 v38, v17
	v_fmamk_f32 v17, v39, 0xbfb8aa3b, v148
	v_exp_f32_e32 v17, v17
	v_sqrt_f32_e32 v21, v21
	v_exp_f32_e32 v23, v23
	v_rcp_f32_e32 v18, v18
	v_add_f32_e32 v17, 1.0, v17
	v_rcp_f32_e32 v17, v17
	v_sqrt_f32_e32 v20, v20
	v_add_f32_e32 v23, 1.0, v23
	v_mul_f32_e32 v154, v19, v21
	v_mul_f32_e32 v17, v17, v149
	v_exp_f32_e32 v17, v17
	v_fmamk_f32 v19, v40, 0xbfb8aa3b, v148
	v_rcp_f32_e32 v23, v23
	v_mul_f32_e32 v153, v18, v20
	v_fma_f32 v151, -v17, v17, 1.0
	v_sqrt_f32_e32 v151, v151
	v_fmamk_f32 v20, v24, 0xbfb8aa3b, v93
	v_fmamk_f32 v22, v22, 0xbfb8aa3b, v93
	v_exp_f32_e32 v19, v19
	v_exp_f32_e32 v20, v20
	v_exp_f32_e32 v22, v22
	v_mul_f32_e32 v18, v23, v151
	v_mul_f32_e32 v7, v7, v18
	v_add_f32_e32 v18, 1.0, v19
	v_rcp_f32_e32 v18, v18
	v_add_f32_e32 v19, 1.0, v20
	v_fmamk_f32 v20, v41, 0xbfb8aa3b, v148
	v_add_f32_e32 v22, 1.0, v22
	v_fma_f32 v39, -v38, v38, 1.0
	v_rcp_f32_e32 v22, v22
	v_sqrt_f32_e32 v39, v39
	v_exp_f32_e32 v20, v20
	v_mul_f32_e32 v18, v18, v149
	v_mul_f32_e32 v21, v22, v39
	v_exp_f32_e32 v39, v18
	v_add_f32_e32 v18, 1.0, v20
	v_rcp_f32_e32 v18, v18
	v_fmamk_f32 v20, v25, 0xbfb8aa3b, v93
	v_exp_f32_e32 v20, v20
	v_mul_f32_e32 v18, v18, v149
	v_exp_f32_e32 v40, v18
	v_fmamk_f32 v18, v42, 0xbfb8aa3b, v148
	v_exp_f32_e32 v18, v18
	v_fmamk_f32 v24, v26, 0xbfb8aa3b, v93
	v_fmamk_f32 v26, v27, 0xbfb8aa3b, v93
	v_add_f32_e32 v20, 1.0, v20
	v_add_f32_e32 v18, 1.0, v18
	v_rcp_f32_e32 v18, v18
	v_fma_f32 v23, -v40, v40, 1.0
	v_fma_f32 v22, -v39, v39, 1.0
	v_mul_f32_e32 v18, v18, v149
	v_exp_f32_e32 v41, v18
	v_fmamk_f32 v18, v43, 0xbfb8aa3b, v148
	v_exp_f32_e32 v18, v18
	v_rcp_f32_e32 v20, v20
	v_sqrt_f32_e32 v23, v23
	v_exp_f32_e32 v26, v26
	v_add_f32_e32 v18, 1.0, v18
	v_rcp_f32_e32 v18, v18
	v_rcp_f32_e32 v19, v19
	v_sqrt_f32_e32 v22, v22
	v_add_f32_e32 v26, 1.0, v26
	v_mul_f32_e32 v18, v18, v149
	v_exp_f32_e32 v18, v18
	v_mul_f32_e32 v43, v20, v23
	v_fmamk_f32 v20, v44, 0xbfb8aa3b, v148
	v_rcp_f32_e32 v26, v26
	v_fma_f32 v27, -v18, v18, 1.0
	v_sqrt_f32_e32 v27, v27
	v_mul_f32_e32 v42, v19, v22
	v_fmamk_f32 v22, v28, 0xbfb8aa3b, v93
	v_exp_f32_e32 v20, v20
	v_exp_f32_e32 v22, v22
	v_mul_f32_e32 v19, v26, v27
	v_mul_f32_e32 v11, v11, v19
	v_add_f32_e32 v19, 1.0, v20
	v_rcp_f32_e32 v19, v19
	v_add_f32_e32 v20, 1.0, v22
	v_fmamk_f32 v22, v45, 0xbfb8aa3b, v148
	v_exp_f32_e32 v22, v22
	v_mul_f32_e32 v19, v19, v149
	v_exp_f32_e32 v44, v19
	v_add_f32_e32 v19, 1.0, v22
	v_rcp_f32_e32 v19, v19
	v_exp_f32_e32 v24, v24
	v_fmamk_f32 v22, v29, 0xbfb8aa3b, v93
	v_mul_f32_e32 v19, v19, v149
	v_exp_f32_e32 v45, v19
	v_fmamk_f32 v19, v46, 0xbfb8aa3b, v148
	v_exp_f32_e32 v19, v19
	v_add_f32_e32 v24, 1.0, v24
	v_fma_f32 v25, -v41, v41, 1.0
	v_add_f32_e32 v19, 1.0, v19
	v_rcp_f32_e32 v19, v19
	v_exp_f32_e32 v22, v22
	v_rcp_f32_e32 v24, v24
	v_sqrt_f32_e32 v25, v25
	v_mul_f32_e32 v19, v19, v149
	v_exp_f32_e32 v46, v19
	v_fmamk_f32 v19, v47, 0xbfb8aa3b, v148
	v_add_f32_e32 v22, 1.0, v22
	v_exp_f32_e32 v19, v19
	v_mul_f32_e32 v151, v24, v25
	v_rcp_f32_e32 v24, v22
	v_fma_f32 v22, -v45, v45, 1.0
	v_sqrt_f32_e32 v25, v22
	v_fmamk_f32 v22, v30, 0xbfb8aa3b, v93
	v_exp_f32_e32 v22, v22
	v_add_f32_e32 v19, 1.0, v19
	v_rcp_f32_e32 v19, v19
	v_fma_f32 v27, -v46, v46, 1.0
	v_add_f32_e32 v22, 1.0, v22
	v_rcp_f32_e32 v26, v22
	v_fmamk_f32 v22, v31, 0xbfb8aa3b, v93
	v_mul_f32_e32 v19, v19, v149
	v_exp_f32_e32 v28, v22
	v_exp_f32_e32 v22, v19
	v_sqrt_f32_e32 v19, v27
	v_fma_f32 v23, -v44, v44, 1.0
	v_add_f32_e32 v27, 1.0, v28
	v_fma_f32 v28, -v22, v22, 1.0
	v_rcp_f32_e32 v27, v27
	v_sqrt_f32_e32 v28, v28
	v_rcp_f32_e32 v20, v20
	v_sqrt_f32_e32 v23, v23
	v_mul_f32_e32 v148, v26, v19
	v_mul_f32_e32 v19, v27, v28
	v_fmac_f32_e32 v7, 0, v17
	v_mul_f32_e32 v15, v15, v19
	v_mul_f32_e32 v19, v38, v7
	v_fmac_f32_e32 v19, v6, v21
	v_fmac_f32_e32 v3, 0, v16
	v_mul_f32_e32 v21, v37, v19
	v_mul_f32_e32 v47, v20, v23
	v_mul_f32_e32 v20, v152, v3
	v_fmac_f32_e32 v21, v5, v154
	v_fmac_f32_e32 v15, 0, v22
	v_mul_f32_e32 v93, v24, v25
	v_fmac_f32_e32 v20, v2, v35
	v_mul_f32_e32 v24, v36, v21
	v_fmac_f32_e32 v11, 0, v18
	v_mul_f32_e32 v2, v46, v15
	v_fmac_f32_e32 v24, v4, v153
	v_mul_f32_e32 v4, v41, v11
	v_fmac_f32_e32 v2, v14, v148
	v_fmac_f32_e32 v4, v10, v151
	v_mul_f32_e32 v5, v45, v2
	v_mul_f32_e32 v23, v150, v20
	v_mul_f32_e32 v6, v40, v4
	v_fmac_f32_e32 v5, v13, v93
	v_fmac_f32_e32 v23, v1, v34
	v_fmac_f32_e32 v6, v9, v43
	v_mul_f32_e32 v14, v22, v46
	v_mul_f32_e32 v9, v44, v5
	v_mul_f32_e32 v25, v33, v23
	v_mul_f32_e32 v13, v45, v14
	v_fmac_f32_e32 v9, v12, v47
	v_fmac_f32_e32 v25, v0, v32
	v_mul_f32_e32 v12, v44, v13
	ds_bpermute_b32 v0, v137, v9
	ds_bpermute_b32 v35, v137, v12
	v_mul_f32_e32 v28, v18, v41
	v_mul_f32_e32 v26, v16, v152
	v_mul_f32_e32 v27, v17, v38
	v_mul_f32_e32 v31, v40, v28
	v_mul_f32_e32 v10, v39, v6
	v_mul_f32_e32 v29, v150, v26
	v_mul_f32_e32 v30, v37, v27
	v_fmac_f32_e32 v10, v8, v42
	v_mul_f32_e32 v34, v39, v31
	v_mul_f32_e32 v32, v33, v29
	v_mul_f32_e32 v33, v36, v30
	s_waitcnt lgkmcnt(1)
	v_cndmask_b32_e64 v36, v0, v9, s[4:5]
	v_cndmask_b32_e64 v37, v9, v0, s[4:5]
	ds_bpermute_b32 v0, v137, v34
	ds_bpermute_b32 v40, v137, v10
	s_waitcnt lgkmcnt(2)
	v_cndmask_b32_e64 v8, v12, v35, s[4:5]
	v_fmac_f32_e32 v37, 0, v8
	ds_bpermute_b32 v8, v137, v33
	v_cndmask_b32_e64 v1, v35, v12, s[4:5]
	v_mul_f32_e32 v38, v12, v35
	v_fmac_f32_e32 v36, v1, v37
	s_waitcnt lgkmcnt(2)
	v_cndmask_b32_e64 v1, v0, v34, s[4:5]
	s_waitcnt lgkmcnt(1)
	v_cndmask_b32_e64 v39, v40, v10, s[4:5]
	v_cndmask_b32_e64 v0, v34, v0, s[4:5]
	v_cndmask_b32_e64 v40, v10, v40, s[4:5]
	ds_bpermute_b32 v44, v137, v24
	v_mul_f32_e32 v41, v38, v0
	v_fmac_f32_e32 v40, v0, v36
	v_mul_f32_e32 v42, v1, v41
	v_fmac_f32_e32 v39, v1, v40
	s_waitcnt lgkmcnt(1)
	v_cndmask_b32_e64 v0, v8, v33, s[4:5]
	v_cndmask_b32_e64 v1, v33, v8, s[4:5]
	ds_bpermute_b32 v8, v137, v32
	ds_bpermute_b32 v47, v137, v25
	s_waitcnt lgkmcnt(2)
	v_cndmask_b32_e64 v43, v44, v24, s[4:5]
	v_cndmask_b32_e64 v44, v24, v44, s[4:5]
	v_mul_f32_e32 v45, v1, v42
	v_fmac_f32_e32 v44, v1, v39
	v_mul_f32_e32 v46, v0, v45
	v_fmac_f32_e32 v43, v0, v44
	s_waitcnt lgkmcnt(1)
	v_cndmask_b32_e64 v0, v32, v8, s[4:5]
	s_waitcnt lgkmcnt(0)
	v_cndmask_b32_e64 v47, v25, v47, s[4:5]
	v_mul_f32_e32 v93, v0, v46
	v_fmac_f32_e32 v47, v0, v43
	s_and_saveexec_b64 s[8:9], s[4:5]
	v_mul_f32_e32 v0, v32, v93
	v_fma_f32 v1, v32, v47, v25
	ds_write_b64 v136, v[0:1] offset:2048
	s_or_b64 exec, exec, s[8:9]
	v_cndmask_b32_e64 v0, 0, 1, s[14:15]
	v_cmp_ne_u32_e64 s[8:9], 1, v0
	s_andn2_b64 vcc, exec, s[14:15]
	s_waitcnt lgkmcnt(0)
	s_barrier
	s_cbranch_vccnz .LBB0_277
	v_add3_u32 v148, v140, v91, s93
	v_mov_b32_e32 v8, 1.0
	v_mov_b32_e32 v1, 0
	s_mov_b32 s12, 7

.LBB0_278:
	ds_read_b128 v[178:181], v145 offset:32768
	ds_read_b128 v[182:185], v147 offset:32768
	v_add_u32_e32 v242, 0x8000, v145
	ds_read_b128 v[186:189], v242 offset:32768
	v_add_u32_e32 v242, 0x8000, v147
	ds_read_b128 v[190:193], v242 offset:32768
	ds_read_b128 v[194:197], v142 offset:32768
	ds_read_b128 v[198:201], v146 offset:32768
	v_add_u32_e32 v242, 0x8000, v146
	ds_read_b128 v[202:205], v242 offset:32768
	v_add_u32_e32 v242, 0x8000, v142
	ds_read_b128 v[206:209], v242 offset:32768
	ds_read_b128 v[210:213], v141 offset:32768
	ds_read_b128 v[214:217], v144 offset:32768
	v_add_u32_e32 v242, 0x8000, v144
	ds_read_b128 v[218:221], v242 offset:32768
	v_add_u32_e32 v242, 0x8000, v141
	ds_read_b128 v[222:225], v242 offset:32768
	ds_read_b128 v[226:229], v139 offset:32768
	ds_read_b128 v[230:233], v143 offset:32768
	v_add_u32_e32 v242, 0x8000, v143
	ds_read_b128 v[234:237], v242 offset:32768
	v_add_u32_e32 v242, 0x8000, v139
	ds_read_b128 v[238:241], v242 offset:32768
	v_cndmask_b32_e64 v0, 1.0, v35, s[4:5]
	v_cndmask_b32_e64 v35, 0, v37, s[4:5]
	v_cndmask_b32_e64 v37, v38, v41, s[4:5]
	v_cndmask_b32_e64 v36, v36, v40, s[4:5]
	v_cndmask_b32_e64 v40, v46, v93, s[4:5]
	v_cndmask_b32_e64 v41, v43, v47, s[4:5]
	v_fmac_f32_e32 v25, v32, v41
	v_mul_f32_e32 v32, v32, v40
	v_fmac_f32_e32 v23, v29, v41
	v_mul_f32_e32 v29, v29, v40
	v_fmac_f32_e32 v20, v26, v41
	v_mul_f32_e32 v26, v26, v40
	v_fmac_f32_e32 v3, v16, v41
	v_mul_f32_e32 v40, v16, v40
	v_mul_f32_e32 v16, v32, v8
	v_fmac_f32_e32 v25, v32, v1
	v_cvt_pk_bf16_f32 v16, v25, v16
	v_cndmask_b32_e64 v38, v42, v45, s[4:5]
	v_cndmask_b32_e64 v39, v39, v44, s[4:5]
	v_fmac_f32_e32 v10, v34, v36
	v_mul_f32_e32 v34, v34, v37
	v_fmac_f32_e32 v6, v31, v36
	v_mul_f32_e32 v31, v31, v37
	v_fmac_f32_e32 v4, v28, v36
	v_mul_f32_e32 v28, v28, v37
	v_fmac_f32_e32 v11, v18, v36
	v_mul_f32_e32 v18, v18, v37
	v_fmac_f32_e32 v9, v12, v35
	v_mul_f32_e32 v36, v0, v12
	v_fmac_f32_e32 v5, v13, v35
	v_mul_f32_e32 v37, v0, v13
	v_lshl_add_u64 v[12:13], v[94:95], 0, s[48:49]
	v_lshl_or_b32 v175, v138, 2, v134
	global_load_dword v172, v175, s[42:43]
	global_load_dword v173, v175, s[36:37]
	global_load_dword v174, v175, s[40:41]
	global_store_dword v[96:97], v16, off offset:128 nt
	v_mul_f32_e32 v16, v29, v8
	v_fmac_f32_e32 v24, v33, v39
	v_mul_f32_e32 v33, v33, v38
	v_fmac_f32_e32 v21, v30, v39
	v_mul_f32_e32 v30, v30, v38
	v_fmac_f32_e32 v19, v27, v39
	v_mul_f32_e32 v27, v27, v38
	v_fmac_f32_e32 v7, v17, v39
	v_mul_f32_e32 v38, v17, v38
	v_fmac_f32_e32 v2, v14, v35
	v_mul_f32_e32 v14, v0, v14
	v_fmac_f32_e32 v15, v22, v35
	v_mul_f32_e32 v0, v0, v22
	v_fmac_f32_e32 v23, v29, v1
	v_cvt_pk_bf16_f32 v22, v23, v16
	v_lshl_add_u64 v[16:17], v[12:13], 0, v[88:89]
	global_store_dword v[16:17], v22, off nt
	v_fmac_f32_e32 v20, v26, v1
	v_mul_f32_e32 v16, v26, v8
	v_cvt_pk_bf16_f32 v20, v20, v16
	v_lshl_add_u64 v[16:17], v[12:13], 0, v[98:99]
	global_store_dword v[16:17], v20, off nt
	v_fmac_f32_e32 v3, v40, v1
	v_mul_f32_e32 v16, v40, v8
	v_cvt_pk_bf16_f32 v3, v3, v16
	v_lshl_add_u64 v[16:17], v[12:13], 0, v[100:101]
	global_store_dword v[16:17], v3, off nt
	v_mul_f32_e32 v3, v33, v8
	v_fmac_f32_e32 v24, v33, v1
	v_cvt_pk_bf16_f32 v3, v24, v3
	v_lshl_add_u64 v[16:17], v[12:13], 0, v[102:103]
	global_store_dword v[16:17], v3, off nt
	v_mul_f32_e32 v3, v30, v8
	v_fmac_f32_e32 v21, v30, v1
	v_cvt_pk_bf16_f32 v3, v21, v3
	v_lshl_add_u64 v[16:17], v[12:13], 0, v[104:105]
	global_store_dword v[16:17], v3, off nt
	v_mul_f32_e32 v3, v27, v8
	v_fmac_f32_e32 v19, v27, v1
	v_cvt_pk_bf16_f32 v3, v19, v3
	v_lshl_add_u64 v[16:17], v[12:13], 0, v[106:107]
	global_store_dword v[16:17], v3, off nt
	v_mul_f32_e32 v3, v38, v8
	v_fmac_f32_e32 v7, v38, v1
	v_cvt_pk_bf16_f32 v3, v7, v3
	v_lshl_add_u64 v[16:17], v[12:13], 0, v[108:109]
	global_store_dword v[16:17], v3, off nt
	v_mul_f32_e32 v3, v34, v8
	v_fmac_f32_e32 v10, v34, v1
	v_cvt_pk_bf16_f32 v3, v10, v3
	v_lshl_add_u64 v[16:17], v[12:13], 0, v[110:111]
	global_store_dword v[16:17], v3, off nt
	v_fmac_f32_e32 v6, v31, v1
	v_mul_f32_e32 v3, v31, v8
	v_cvt_pk_bf16_f32 v3, v6, v3
	v_lshl_add_u64 v[6:7], v[12:13], 0, v[112:113]
	global_store_dword v[6:7], v3, off nt
	v_mul_f32_e32 v3, v28, v8
	v_fmac_f32_e32 v4, v28, v1
	v_cvt_pk_bf16_f32 v3, v4, v3
	v_lshl_add_u64 v[6:7], v[12:13], 0, v[114:115]
	global_store_dword v[6:7], v3, off nt
	v_mul_f32_e32 v3, v18, v8
	v_fmac_f32_e32 v11, v18, v1
	v_cvt_pk_bf16_f32 v3, v11, v3
	v_lshl_add_u64 v[6:7], v[12:13], 0, v[116:117]
	global_store_dword v[6:7], v3, off nt
	v_mul_f32_e32 v3, v36, v8
	v_fmac_f32_e32 v9, v36, v1
	v_cvt_pk_bf16_f32 v3, v9, v3
	v_lshl_add_u64 v[6:7], v[12:13], 0, v[118:119]
	global_store_dword v[6:7], v3, off nt
	v_fmac_f32_e32 v5, v37, v1
	v_mul_f32_e32 v3, v37, v8
	v_cvt_pk_bf16_f32 v3, v5, v3
	v_lshl_add_u64 v[4:5], v[12:13], 0, v[120:121]
	global_store_dword v[4:5], v3, off nt
	v_fmac_f32_e32 v2, v14, v1
	v_mul_f32_e32 v3, v14, v8
	v_cvt_pk_bf16_f32 v4, v2, v3
	v_lshl_add_u64 v[2:3], v[12:13], 0, v[122:123]
	v_fmac_f32_e32 v15, v0, v1
	v_mul_f32_e32 v0, v0, v8
	global_store_dword v[2:3], v4, off nt
	v_cvt_pk_bf16_f32 v2, v15, v0
	v_lshl_add_u64 v[0:1], v[12:13], 0, v[124:125]
	global_store_dword v[0:1], v2, off nt
	s_and_saveexec_b64 s[12:13], s[6:7]
	s_cbranch_execz .LBB0_280
	v_add_u32_e32 v12, 0x800, v90
	ds_read2_b64 v[0:3], v12 offset0:192 offset1:224
	ds_read2_b64 v[4:7], v12 offset0:128 offset1:160
	ds_read2_b64 v[8:11], v12 offset0:64 offset1:96
	ds_read2_b64 v[12:15], v12 offset1:32
	s_waitcnt lgkmcnt(3)
	v_fma_f32 v16, 0, v2, v3
	v_pk_mul_f32 v[2:3], v[2:3], v[0:1]
	v_fma_f32 v0, v0, v16, v1
	s_waitcnt lgkmcnt(2)
	v_fma_f32 v0, v6, v0, v7
	v_fma_f32 v0, v4, v0, v5
	s_waitcnt lgkmcnt(1)
	v_fma_f32 v1, v10, v0, v11
	v_mov_b32_e32 v0, v2
	v_mov_b32_e32 v16, v6
	v_mov_b32_e32 v17, v8
	v_pk_mul_f32 v[2:3], v[2:3], v[6:7]
	v_pk_fma_f32 v[0:1], v[0:1], v[16:17], v[8:9]
	v_pk_mul_f32 v[2:3], v[2:3], v[4:5]
	s_waitcnt lgkmcnt(0)
	v_mov_b32_e32 v11, v14
	v_mov_b32_e32 v3, v1
	v_pk_mul_f32 v[0:1], v[2:3], v[10:11]
	v_pk_fma_f32 v[2:3], v[2:3], v[10:11], v[14:15]
	v_pk_mul_f32 v[0:1], v[0:1], v[8:9]
	v_mov_b32_e32 v4, v14
	v_mov_b32_e32 v2, v0
	v_mov_b32_e32 v5, v12
	v_pk_mul_f32 v[0:1], v[0:1], v[14:15]
	v_pk_fma_f32 v[2:3], v[2:3], v[4:5], v[12:13]
	v_pk_mul_f32 v[0:1], v[0:1], v[12:13]
	v_add_u32_e32 v2, 32, v92
	v_mov_b32_e32 v1, v3
	v_ashrrev_i32_e32 v3, 31, v2
	v_lshl_add_u64 v[2:3], v[2:3], 3, s[30:31]
	global_store_dwordx2 v[2:3], v[0:1], off
.LBB0_280:
	s_or_b64 exec, exec, s[12:13]
	s_setprio 1
	s_waitcnt lgkmcnt(0)
	v_mfma_f32_32x32x16_bf16 v[32:47], v[48:51], v[178:181], 0
	v_mfma_f32_32x32x16_bf16 v[16:31], v[48:51], v[186:189], 0
	v_mfma_f32_32x32x16_bf16 v[32:47], v[52:55], v[182:185], v[32:47]
	v_mfma_f32_32x32x16_bf16 v[16:31], v[52:55], v[190:193], v[16:31]
	v_mfma_f32_32x32x16_bf16 v[32:47], v[56:59], v[194:197], v[32:47]
	v_mfma_f32_32x32x16_bf16 v[16:31], v[56:59], v[206:209], v[16:31]
	v_mfma_f32_32x32x16_bf16 v[32:47], v[60:63], v[198:201], v[32:47]
	v_mfma_f32_32x32x16_bf16 v[16:31], v[60:63], v[202:205], v[16:31]
	v_mfma_f32_32x32x16_bf16 v[32:47], v[64:67], v[210:213], v[32:47]
	v_mfma_f32_32x32x16_bf16 v[16:31], v[64:67], v[222:225], v[16:31]
	v_mfma_f32_32x32x16_bf16 v[32:47], v[68:71], v[214:217], v[32:47]
	v_mfma_f32_32x32x16_bf16 v[16:31], v[68:71], v[218:221], v[16:31]
	v_mfma_f32_32x32x16_bf16 v[32:47], v[72:75], v[226:229], v[32:47]
	v_mfma_f32_32x32x16_bf16 v[16:31], v[72:75], v[238:241], v[16:31]
	v_mfma_f32_32x32x16_bf16 v[32:47], v[76:79], v[230:233], v[32:47]
	v_mfma_f32_32x32x16_bf16 v[16:31], v[76:79], v[234:237], v[16:31]
	v_mfma_f32_32x32x16_bf16 v[0:15], v[64:67], v[80:83], 0
	v_mfma_f32_32x32x16_bf16 v[0:15], v[68:71], v[84:87], v[0:15]
	s_setprio 0
	v_lshl_or_b32 v93, v138, 2, v134
	s_waitcnt vmcnt(16)
	ds_read_b32 v251, v167 offset:256
	v_mul_f32_e32 v148, 0xbfb8aa3b, v173
	v_mul_f32_e32 v93, 0xbfb8aa3b, v174
	v_fmamk_f32 v32, v32, 0xbfb8aa3b, v148
	v_fmamk_f32 v16, v16, 0xbfb8aa3b, v93
	v_exp_f32_e32 v32, v32
	v_exp_f32_e32 v150, v16
	v_fmamk_f32 v17, v17, 0xbfb8aa3b, v93
	v_exp_f32_e32 v151, v17
	v_add_f32_e32 v32, 1.0, v32
	v_add_f32_e32 v150, 1.0, v150
	v_rcp_f32_e32 v17, v32
	v_rcp_f32_e32 v32, v150
	v_fmamk_f32 v33, v33, 0xbfb8aa3b, v148
	v_fmamk_f32 v34, v34, 0xbfb8aa3b, v148
	v_exp_f32_e32 v33, v33
	v_exp_f32_e32 v34, v34
	v_add_f32_e32 v33, 1.0, v33
	v_add_f32_e32 v34, 1.0, v34
	v_rcp_f32_e32 v33, v33
	v_rcp_f32_e32 v34, v34
	v_fmamk_f32 v18, v18, 0xbfb8aa3b, v93
	v_fmamk_f32 v19, v19, 0xbfb8aa3b, v93
	v_exp_f32_e32 v18, v18
	s_waitcnt lgkmcnt(0)
	v_mul_f32_e32 v149, 0x3fb8aa3b, v251
	v_mul_f32_e32 v16, v17, v149
	v_mul_f32_e32 v17, v33, v149
	v_exp_f32_e32 v33, v16
	v_mul_f32_e32 v16, v34, v149
	v_exp_f32_e32 v152, v16
	v_fmamk_f32 v16, v35, 0xbfb8aa3b, v148
	v_exp_f32_e32 v16, v16
	v_exp_f32_e32 v150, v17
	v_add_f32_e32 v16, 1.0, v16
	v_rcp_f32_e32 v16, v16
	v_exp_f32_e32 v19, v19
	v_add_f32_e32 v151, 1.0, v151
	v_add_f32_e32 v18, 1.0, v18
	v_mul_f32_e32 v16, v16, v149
	v_exp_f32_e32 v16, v16
	v_fma_f32 v35, -v152, v152, 1.0
	v_rcp_f32_e32 v17, v151
	v_fma_f32 v34, -v33, v33, 1.0
	v_fma_f32 v151, -v150, v150, 1.0
	v_rcp_f32_e32 v18, v18
	v_sqrt_f32_e32 v35, v35
	v_add_f32_e32 v19, 1.0, v19
	v_fma_f32 v153, -v16, v16, 1.0
	v_sqrt_f32_e32 v34, v34
	v_sqrt_f32_e32 v151, v151
	v_rcp_f32_e32 v19, v19
	v_sqrt_f32_e32 v153, v153
	v_mul_f32_e32 v35, v18, v35
	v_fmamk_f32 v18, v36, 0xbfb8aa3b, v148
	v_mul_f32_e32 v32, v32, v34
	v_mul_f32_e32 v34, v17, v151
	v_mul_f32_e32 v17, v19, v153
	v_fmamk_f32 v19, v20, 0xbfb8aa3b, v93
	v_exp_f32_e32 v18, v18
	v_exp_f32_e32 v19, v19
	v_mul_f32_e32 v3, v3, v17
	v_add_f32_e32 v17, 1.0, v18
	v_rcp_f32_e32 v17, v17
	v_add_f32_e32 v18, 1.0, v19
	v_fmamk_f32 v19, v37, 0xbfb8aa3b, v148
	v_exp_f32_e32 v19, v19
	v_mul_f32_e32 v17, v17, v149
	v_exp_f32_e32 v36, v17
	v_add_f32_e32 v17, 1.0, v19
	v_rcp_f32_e32 v17, v17
	v_fmamk_f32 v19, v21, 0xbfb8aa3b, v93
	v_exp_f32_e32 v19, v19
	v_mul_f32_e32 v17, v17, v149
	v_exp_f32_e32 v37, v17
	v_fmamk_f32 v17, v38, 0xbfb8aa3b, v148
	v_exp_f32_e32 v17, v17
	v_fmamk_f32 v23, v23, 0xbfb8aa3b, v93
	v_add_f32_e32 v19, 1.0, v19
	v_fma_f32 v21, -v37, v37, 1.0
	v_add_f32_e32 v17, 1.0, v17
	v_rcp_f32_e32 v17, v17
	v_fma_f32 v20, -v36, v36, 1.0
	v_rcp_f32_e32 v19, v19
	v_mul_f32_e32 v17, v17, v149
	v_exp_f32_e32 v38, v17
	v_fmamk_f32 v17, v39, 0xbfb8aa3b, v148
	v_exp_f32_e32 v17, v17
	v_sqrt_f32_e32 v21, v21
	v_exp_f32_e32 v23, v23
	v_rcp_f32_e32 v18, v18
	v_add_f32_e32 v17, 1.0, v17
	v_rcp_f32_e32 v17, v17
	v_sqrt_f32_e32 v20, v20
	v_add_f32_e32 v23, 1.0, v23
	v_mul_f32_e32 v154, v19, v21
	v_mul_f32_e32 v17, v17, v149
	v_exp_f32_e32 v17, v17
	v_fmamk_f32 v19, v40, 0xbfb8aa3b, v148
	v_rcp_f32_e32 v23, v23
	v_mul_f32_e32 v153, v18, v20
	v_fma_f32 v151, -v17, v17, 1.0
	v_sqrt_f32_e32 v151, v151
	v_fmamk_f32 v20, v24, 0xbfb8aa3b, v93
	v_fmamk_f32 v22, v22, 0xbfb8aa3b, v93
	v_exp_f32_e32 v19, v19
	v_exp_f32_e32 v20, v20
	v_exp_f32_e32 v22, v22
	v_mul_f32_e32 v18, v23, v151
	v_mul_f32_e32 v7, v7, v18
	v_add_f32_e32 v18, 1.0, v19
	v_rcp_f32_e32 v18, v18
	v_add_f32_e32 v19, 1.0, v20
	v_fmamk_f32 v20, v41, 0xbfb8aa3b, v148
	v_add_f32_e32 v22, 1.0, v22
	v_fma_f32 v39, -v38, v38, 1.0
	v_rcp_f32_e32 v22, v22
	v_sqrt_f32_e32 v39, v39
	v_exp_f32_e32 v20, v20
	v_mul_f32_e32 v18, v18, v149
	v_mul_f32_e32 v21, v22, v39
	v_exp_f32_e32 v39, v18
	v_add_f32_e32 v18, 1.0, v20
	v_rcp_f32_e32 v18, v18
	v_fmamk_f32 v20, v25, 0xbfb8aa3b, v93
	v_exp_f32_e32 v20, v20
	v_mul_f32_e32 v18, v18, v149
	v_exp_f32_e32 v40, v18
	v_fmamk_f32 v18, v42, 0xbfb8aa3b, v148
	v_exp_f32_e32 v18, v18
	v_fmamk_f32 v24, v26, 0xbfb8aa3b, v93
	v_fmamk_f32 v26, v27, 0xbfb8aa3b, v93
	v_add_f32_e32 v20, 1.0, v20
	v_add_f32_e32 v18, 1.0, v18
	v_rcp_f32_e32 v18, v18
	v_fma_f32 v23, -v40, v40, 1.0
	v_fma_f32 v22, -v39, v39, 1.0
	v_mul_f32_e32 v18, v18, v149
	v_exp_f32_e32 v41, v18
	v_fmamk_f32 v18, v43, 0xbfb8aa3b, v148
	v_exp_f32_e32 v18, v18
	v_rcp_f32_e32 v20, v20
	v_sqrt_f32_e32 v23, v23
	v_exp_f32_e32 v26, v26
	v_add_f32_e32 v18, 1.0, v18
	v_rcp_f32_e32 v18, v18
	v_rcp_f32_e32 v19, v19
	v_sqrt_f32_e32 v22, v22
	v_add_f32_e32 v26, 1.0, v26
	v_mul_f32_e32 v18, v18, v149
	v_exp_f32_e32 v18, v18
	v_mul_f32_e32 v43, v20, v23
	v_fmamk_f32 v20, v44, 0xbfb8aa3b, v148
	v_rcp_f32_e32 v26, v26
	v_fma_f32 v27, -v18, v18, 1.0
	v_sqrt_f32_e32 v27, v27
	v_mul_f32_e32 v42, v19, v22
	v_fmamk_f32 v22, v28, 0xbfb8aa3b, v93
	v_exp_f32_e32 v20, v20
	v_exp_f32_e32 v22, v22
	v_mul_f32_e32 v19, v26, v27
	v_mul_f32_e32 v11, v11, v19
	v_add_f32_e32 v19, 1.0, v20
	v_rcp_f32_e32 v19, v19
	v_add_f32_e32 v20, 1.0, v22
	v_fmamk_f32 v22, v45, 0xbfb8aa3b, v148
	v_exp_f32_e32 v22, v22
	v_mul_f32_e32 v19, v19, v149
	v_exp_f32_e32 v44, v19
	v_add_f32_e32 v19, 1.0, v22
	v_rcp_f32_e32 v19, v19
	v_exp_f32_e32 v24, v24
	v_fmamk_f32 v22, v29, 0xbfb8aa3b, v93
	v_mul_f32_e32 v19, v19, v149
	v_exp_f32_e32 v45, v19
	v_fmamk_f32 v19, v46, 0xbfb8aa3b, v148
	v_exp_f32_e32 v19, v19
	v_add_f32_e32 v24, 1.0, v24
	v_fma_f32 v25, -v41, v41, 1.0
	v_add_f32_e32 v19, 1.0, v19
	v_rcp_f32_e32 v19, v19
	v_exp_f32_e32 v22, v22
	v_rcp_f32_e32 v24, v24
	v_sqrt_f32_e32 v25, v25
	v_mul_f32_e32 v19, v19, v149
	v_exp_f32_e32 v46, v19
	v_fmamk_f32 v19, v47, 0xbfb8aa3b, v148
	v_add_f32_e32 v22, 1.0, v22
	v_exp_f32_e32 v19, v19
	v_mul_f32_e32 v151, v24, v25
	v_rcp_f32_e32 v24, v22
	v_fma_f32 v22, -v45, v45, 1.0
	v_sqrt_f32_e32 v25, v22
	v_fmamk_f32 v22, v30, 0xbfb8aa3b, v93
	v_exp_f32_e32 v22, v22
	v_add_f32_e32 v19, 1.0, v19
	v_rcp_f32_e32 v19, v19
	v_fma_f32 v27, -v46, v46, 1.0
	v_add_f32_e32 v22, 1.0, v22
	v_rcp_f32_e32 v26, v22
	v_fmamk_f32 v22, v31, 0xbfb8aa3b, v93
	v_mul_f32_e32 v19, v19, v149
	v_exp_f32_e32 v28, v22
	v_exp_f32_e32 v22, v19
	v_sqrt_f32_e32 v19, v27
	v_fma_f32 v23, -v44, v44, 1.0
	v_add_f32_e32 v27, 1.0, v28
	v_fma_f32 v28, -v22, v22, 1.0
	v_rcp_f32_e32 v27, v27
	v_sqrt_f32_e32 v28, v28
	v_rcp_f32_e32 v20, v20
	v_sqrt_f32_e32 v23, v23
	v_mul_f32_e32 v148, v26, v19
	v_mul_f32_e32 v19, v27, v28
	v_fmac_f32_e32 v7, 0, v17
	v_mul_f32_e32 v15, v15, v19
	v_mul_f32_e32 v19, v38, v7
	v_fmac_f32_e32 v19, v6, v21
	v_fmac_f32_e32 v3, 0, v16
	v_mul_f32_e32 v21, v37, v19
	v_mul_f32_e32 v47, v20, v23
	v_mul_f32_e32 v20, v152, v3
	v_fmac_f32_e32 v21, v5, v154
	v_fmac_f32_e32 v15, 0, v22
	v_mul_f32_e32 v93, v24, v25
	v_fmac_f32_e32 v20, v2, v35
	v_mul_f32_e32 v24, v36, v21
	v_fmac_f32_e32 v11, 0, v18
	v_mul_f32_e32 v2, v46, v15
	v_fmac_f32_e32 v24, v4, v153
	v_mul_f32_e32 v4, v41, v11
	v_fmac_f32_e32 v2, v14, v148
	v_fmac_f32_e32 v4, v10, v151
	v_mul_f32_e32 v5, v45, v2
	v_mul_f32_e32 v23, v150, v20
	v_mul_f32_e32 v6, v40, v4
	v_fmac_f32_e32 v5, v13, v93
	v_fmac_f32_e32 v23, v1, v34
	v_fmac_f32_e32 v6, v9, v43
	v_mul_f32_e32 v14, v22, v46
	v_mul_f32_e32 v9, v44, v5
	v_mul_f32_e32 v25, v33, v23
	v_mul_f32_e32 v13, v45, v14
	v_fmac_f32_e32 v9, v12, v47
	v_fmac_f32_e32 v25, v0, v32
	v_mul_f32_e32 v12, v44, v13
	ds_bpermute_b32 v0, v137, v9
	ds_bpermute_b32 v35, v137, v12
	v_mul_f32_e32 v28, v18, v41
	v_mul_f32_e32 v26, v16, v152
	v_mul_f32_e32 v27, v17, v38
	v_mul_f32_e32 v31, v40, v28
	v_mul_f32_e32 v10, v39, v6
	v_mul_f32_e32 v29, v150, v26
	v_mul_f32_e32 v30, v37, v27
	v_fmac_f32_e32 v10, v8, v42
	v_mul_f32_e32 v34, v39, v31
	v_mul_f32_e32 v32, v33, v29
	v_mul_f32_e32 v33, v36, v30
	s_waitcnt lgkmcnt(1)
	v_cndmask_b32_e64 v36, v0, v9, s[4:5]
	v_cndmask_b32_e64 v37, v9, v0, s[4:5]
	ds_bpermute_b32 v0, v137, v34
	ds_bpermute_b32 v40, v137, v10
	s_waitcnt lgkmcnt(2)
	v_cndmask_b32_e64 v8, v12, v35, s[4:5]
	v_fmac_f32_e32 v37, 0, v8
	ds_bpermute_b32 v8, v137, v33
	v_cndmask_b32_e64 v1, v35, v12, s[4:5]
	v_mul_f32_e32 v38, v12, v35
	v_fmac_f32_e32 v36, v1, v37
	s_waitcnt lgkmcnt(2)
	v_cndmask_b32_e64 v1, v0, v34, s[4:5]
	s_waitcnt lgkmcnt(1)
	v_cndmask_b32_e64 v39, v40, v10, s[4:5]
	v_cndmask_b32_e64 v0, v34, v0, s[4:5]
	v_cndmask_b32_e64 v40, v10, v40, s[4:5]
	ds_bpermute_b32 v44, v137, v24
	v_mul_f32_e32 v41, v38, v0
	v_fmac_f32_e32 v40, v0, v36
	v_mul_f32_e32 v42, v1, v41
	v_fmac_f32_e32 v39, v1, v40
	s_waitcnt lgkmcnt(1)
	v_cndmask_b32_e64 v0, v8, v33, s[4:5]
	v_cndmask_b32_e64 v1, v33, v8, s[4:5]
	ds_bpermute_b32 v8, v137, v32
	ds_bpermute_b32 v47, v137, v25
	s_waitcnt lgkmcnt(2)
	v_cndmask_b32_e64 v43, v44, v24, s[4:5]
	v_cndmask_b32_e64 v44, v24, v44, s[4:5]
	v_mul_f32_e32 v45, v1, v42
	v_fmac_f32_e32 v44, v1, v39
	v_mul_f32_e32 v46, v0, v45
	v_fmac_f32_e32 v43, v0, v44
	s_waitcnt lgkmcnt(1)
	v_cndmask_b32_e64 v0, v32, v8, s[4:5]
	s_waitcnt lgkmcnt(0)
	v_cndmask_b32_e64 v47, v25, v47, s[4:5]
	v_mul_f32_e32 v93, v0, v46
	v_fmac_f32_e32 v47, v0, v43
	s_and_saveexec_b64 s[12:13], s[4:5]
	v_mul_f32_e32 v0, v32, v93
	v_fma_f32 v1, v32, v47, v25
	ds_write_b64 v136, v[0:1] offset:4096
	s_or_b64 exec, exec, s[12:13]
	s_and_b64 vcc, exec, s[8:9]
	s_waitcnt lgkmcnt(0)
	s_barrier
	s_cbranch_vccnz .LBB0_285
	v_add3_u32 v148, v140, v91, s94
	v_mov_b32_e32 v8, 1.0
	v_mov_b32_e32 v1, 0
	s_mov_b32 s12, 7

.LBB0_286:
	ds_read_b128 v[178:181], v145 offset:40960
	ds_read_b128 v[182:185], v147 offset:40960
	v_add_u32_e32 v242, 0xa000, v145
	ds_read_b128 v[186:189], v242 offset:32768
	v_add_u32_e32 v242, 0xa000, v147
	ds_read_b128 v[190:193], v242 offset:32768
	ds_read_b128 v[194:197], v142 offset:40960
	ds_read_b128 v[198:201], v146 offset:40960
	v_add_u32_e32 v242, 0xa000, v146
	ds_read_b128 v[202:205], v242 offset:32768
	v_add_u32_e32 v242, 0xa000, v142
	ds_read_b128 v[206:209], v242 offset:32768
	ds_read_b128 v[210:213], v141 offset:40960
	ds_read_b128 v[214:217], v144 offset:40960
	v_add_u32_e32 v242, 0xa000, v144
	ds_read_b128 v[218:221], v242 offset:32768
	v_add_u32_e32 v242, 0xa000, v141
	ds_read_b128 v[222:225], v242 offset:32768
	ds_read_b128 v[226:229], v139 offset:40960
	ds_read_b128 v[230:233], v143 offset:40960
	v_add_u32_e32 v242, 0xa000, v143
	ds_read_b128 v[234:237], v242 offset:32768
	v_add_u32_e32 v242, 0xa000, v139
	ds_read_b128 v[238:241], v242 offset:32768
	v_cndmask_b32_e64 v0, 1.0, v35, s[4:5]
	v_cndmask_b32_e64 v35, 0, v37, s[4:5]
	v_cndmask_b32_e64 v37, v38, v41, s[4:5]
	v_cndmask_b32_e64 v36, v36, v40, s[4:5]
	v_cndmask_b32_e64 v40, v46, v93, s[4:5]
	v_cndmask_b32_e64 v41, v43, v47, s[4:5]
	v_fmac_f32_e32 v25, v32, v41
	v_mul_f32_e32 v32, v32, v40
	v_fmac_f32_e32 v23, v29, v41
	v_mul_f32_e32 v29, v29, v40
	v_fmac_f32_e32 v20, v26, v41
	v_mul_f32_e32 v26, v26, v40
	v_fmac_f32_e32 v3, v16, v41
	v_mul_f32_e32 v40, v16, v40
	v_mul_f32_e32 v16, v32, v8
	v_fmac_f32_e32 v25, v32, v1
	v_cvt_pk_bf16_f32 v16, v25, v16
	v_cndmask_b32_e64 v38, v42, v45, s[4:5]
	v_cndmask_b32_e64 v39, v39, v44, s[4:5]
	v_fmac_f32_e32 v10, v34, v36
	v_mul_f32_e32 v34, v34, v37
	v_fmac_f32_e32 v6, v31, v36
	v_mul_f32_e32 v31, v31, v37
	v_fmac_f32_e32 v4, v28, v36
	v_mul_f32_e32 v28, v28, v37
	v_fmac_f32_e32 v11, v18, v36
	v_mul_f32_e32 v18, v18, v37
	v_fmac_f32_e32 v9, v12, v35
	v_mul_f32_e32 v36, v0, v12
	v_fmac_f32_e32 v5, v13, v35
	v_mul_f32_e32 v37, v0, v13
	v_lshl_add_u64 v[12:13], v[94:95], 0, s[60:61]
	v_lshl_or_b32 v175, v138, 2, v135
	global_load_dword v172, v175, s[42:43]
	global_load_dword v173, v175, s[36:37]
	global_load_dword v174, v175, s[40:41]
	global_store_dword v[96:97], v16, off offset:256 nt
	v_mul_f32_e32 v16, v29, v8
	v_fmac_f32_e32 v24, v33, v39
	v_mul_f32_e32 v33, v33, v38
	v_fmac_f32_e32 v21, v30, v39
	v_mul_f32_e32 v30, v30, v38
	v_fmac_f32_e32 v19, v27, v39
	v_mul_f32_e32 v27, v27, v38
	v_fmac_f32_e32 v7, v17, v39
	v_mul_f32_e32 v38, v17, v38
	v_fmac_f32_e32 v2, v14, v35
	v_mul_f32_e32 v14, v0, v14
	v_fmac_f32_e32 v15, v22, v35
	v_mul_f32_e32 v0, v0, v22
	v_fmac_f32_e32 v23, v29, v1
	v_cvt_pk_bf16_f32 v22, v23, v16
	v_lshl_add_u64 v[16:17], v[12:13], 0, v[88:89]
	global_store_dword v[16:17], v22, off nt
	v_fmac_f32_e32 v20, v26, v1
	v_mul_f32_e32 v16, v26, v8
	v_cvt_pk_bf16_f32 v20, v20, v16
	v_lshl_add_u64 v[16:17], v[12:13], 0, v[98:99]
	global_store_dword v[16:17], v20, off nt
	v_fmac_f32_e32 v3, v40, v1
	v_mul_f32_e32 v16, v40, v8
	v_cvt_pk_bf16_f32 v3, v3, v16
	v_lshl_add_u64 v[16:17], v[12:13], 0, v[100:101]
	global_store_dword v[16:17], v3, off nt
	v_mul_f32_e32 v3, v33, v8
	v_fmac_f32_e32 v24, v33, v1
	v_cvt_pk_bf16_f32 v3, v24, v3
	v_lshl_add_u64 v[16:17], v[12:13], 0, v[102:103]
	global_store_dword v[16:17], v3, off nt
	v_mul_f32_e32 v3, v30, v8
	v_fmac_f32_e32 v21, v30, v1
	v_cvt_pk_bf16_f32 v3, v21, v3
	v_lshl_add_u64 v[16:17], v[12:13], 0, v[104:105]
	global_store_dword v[16:17], v3, off nt
	v_mul_f32_e32 v3, v27, v8
	v_fmac_f32_e32 v19, v27, v1
	v_cvt_pk_bf16_f32 v3, v19, v3
	v_lshl_add_u64 v[16:17], v[12:13], 0, v[106:107]
	global_store_dword v[16:17], v3, off nt
	v_mul_f32_e32 v3, v38, v8
	v_fmac_f32_e32 v7, v38, v1
	v_cvt_pk_bf16_f32 v3, v7, v3
	v_lshl_add_u64 v[16:17], v[12:13], 0, v[108:109]
	global_store_dword v[16:17], v3, off nt
	v_mul_f32_e32 v3, v34, v8
	v_fmac_f32_e32 v10, v34, v1
	v_cvt_pk_bf16_f32 v3, v10, v3
	v_lshl_add_u64 v[16:17], v[12:13], 0, v[110:111]
	global_store_dword v[16:17], v3, off nt
	v_fmac_f32_e32 v6, v31, v1
	v_mul_f32_e32 v3, v31, v8
	v_cvt_pk_bf16_f32 v3, v6, v3
	v_lshl_add_u64 v[6:7], v[12:13], 0, v[112:113]
	global_store_dword v[6:7], v3, off nt
	v_mul_f32_e32 v3, v28, v8
	v_fmac_f32_e32 v4, v28, v1
	v_cvt_pk_bf16_f32 v3, v4, v3
	v_lshl_add_u64 v[6:7], v[12:13], 0, v[114:115]
	global_store_dword v[6:7], v3, off nt
	v_mul_f32_e32 v3, v18, v8
	v_fmac_f32_e32 v11, v18, v1
	v_cvt_pk_bf16_f32 v3, v11, v3
	v_lshl_add_u64 v[6:7], v[12:13], 0, v[116:117]
	global_store_dword v[6:7], v3, off nt
	v_mul_f32_e32 v3, v36, v8
	v_fmac_f32_e32 v9, v36, v1
	v_cvt_pk_bf16_f32 v3, v9, v3
	v_lshl_add_u64 v[6:7], v[12:13], 0, v[118:119]
	global_store_dword v[6:7], v3, off nt
	v_fmac_f32_e32 v5, v37, v1
	v_mul_f32_e32 v3, v37, v8
	v_cvt_pk_bf16_f32 v3, v5, v3
	v_lshl_add_u64 v[4:5], v[12:13], 0, v[120:121]
	global_store_dword v[4:5], v3, off nt
	v_fmac_f32_e32 v2, v14, v1
	v_mul_f32_e32 v3, v14, v8
	v_cvt_pk_bf16_f32 v4, v2, v3
	v_lshl_add_u64 v[2:3], v[12:13], 0, v[122:123]
	v_fmac_f32_e32 v15, v0, v1
	v_mul_f32_e32 v0, v0, v8
	global_store_dword v[2:3], v4, off nt
	v_cvt_pk_bf16_f32 v2, v15, v0
	v_lshl_add_u64 v[0:1], v[12:13], 0, v[124:125]
	global_store_dword v[0:1], v2, off nt
	s_and_saveexec_b64 s[12:13], s[6:7]
	s_cbranch_execz .LBB0_288
	v_add_u32_e32 v12, 0x1000, v90
	ds_read2_b64 v[0:3], v12 offset0:192 offset1:224
	ds_read2_b64 v[4:7], v12 offset0:128 offset1:160
	ds_read2_b64 v[8:11], v12 offset0:64 offset1:96
	ds_read2_b64 v[12:15], v12 offset1:32
	s_waitcnt lgkmcnt(3)
	v_fma_f32 v16, 0, v2, v3
	v_pk_mul_f32 v[2:3], v[2:3], v[0:1]
	v_fma_f32 v0, v0, v16, v1
	s_waitcnt lgkmcnt(2)
	v_fma_f32 v0, v6, v0, v7
	v_fma_f32 v0, v4, v0, v5
	s_waitcnt lgkmcnt(1)
	v_fma_f32 v1, v10, v0, v11
	v_mov_b32_e32 v0, v2
	v_mov_b32_e32 v16, v6
	v_mov_b32_e32 v17, v8
	v_pk_mul_f32 v[2:3], v[2:3], v[6:7]
	v_pk_fma_f32 v[0:1], v[0:1], v[16:17], v[8:9]
	v_pk_mul_f32 v[2:3], v[2:3], v[4:5]
	s_waitcnt lgkmcnt(0)
	v_mov_b32_e32 v11, v14
	v_mov_b32_e32 v3, v1
	v_pk_mul_f32 v[0:1], v[2:3], v[10:11]
	v_pk_fma_f32 v[2:3], v[2:3], v[10:11], v[14:15]
	v_pk_mul_f32 v[0:1], v[0:1], v[8:9]
	v_mov_b32_e32 v4, v14
	v_mov_b32_e32 v2, v0
	v_mov_b32_e32 v5, v12
	v_pk_mul_f32 v[0:1], v[0:1], v[14:15]
	v_pk_fma_f32 v[2:3], v[2:3], v[4:5], v[12:13]
	v_pk_mul_f32 v[0:1], v[0:1], v[12:13]
	v_add_u32_e32 v2, 64, v92
	v_mov_b32_e32 v1, v3
	v_ashrrev_i32_e32 v3, 31, v2
	v_lshl_add_u64 v[2:3], v[2:3], 3, s[30:31]
	global_store_dwordx2 v[2:3], v[0:1], off
.LBB0_288:
	s_or_b64 exec, exec, s[12:13]
	s_setprio 1
	s_waitcnt lgkmcnt(0)
	v_mfma_f32_32x32x16_bf16 v[32:47], v[48:51], v[178:181], 0
	v_mfma_f32_32x32x16_bf16 v[16:31], v[48:51], v[186:189], 0
	v_mfma_f32_32x32x16_bf16 v[32:47], v[52:55], v[182:185], v[32:47]
	v_mfma_f32_32x32x16_bf16 v[16:31], v[52:55], v[190:193], v[16:31]
	v_mfma_f32_32x32x16_bf16 v[32:47], v[56:59], v[194:197], v[32:47]
	v_mfma_f32_32x32x16_bf16 v[16:31], v[56:59], v[206:209], v[16:31]
	v_mfma_f32_32x32x16_bf16 v[32:47], v[60:63], v[198:201], v[32:47]
	v_mfma_f32_32x32x16_bf16 v[16:31], v[60:63], v[202:205], v[16:31]
	v_mfma_f32_32x32x16_bf16 v[32:47], v[64:67], v[210:213], v[32:47]
	v_mfma_f32_32x32x16_bf16 v[16:31], v[64:67], v[222:225], v[16:31]
	v_mfma_f32_32x32x16_bf16 v[32:47], v[68:71], v[214:217], v[32:47]
	v_mfma_f32_32x32x16_bf16 v[16:31], v[68:71], v[218:221], v[16:31]
	v_mfma_f32_32x32x16_bf16 v[32:47], v[72:75], v[226:229], v[32:47]
	v_mfma_f32_32x32x16_bf16 v[16:31], v[72:75], v[238:241], v[16:31]
	v_mfma_f32_32x32x16_bf16 v[32:47], v[76:79], v[230:233], v[32:47]
	v_mfma_f32_32x32x16_bf16 v[16:31], v[76:79], v[234:237], v[16:31]
	v_mfma_f32_32x32x16_bf16 v[0:15], v[72:75], v[80:83], 0
	v_mfma_f32_32x32x16_bf16 v[0:15], v[76:79], v[84:87], v[0:15]
	s_setprio 0
	v_lshl_or_b32 v48, v138, 2, v135
	s_waitcnt vmcnt(16)
	ds_read_b32 v251, v167 offset:384
	v_mul_f32_e32 v49, 0xbfb8aa3b, v173
	v_mul_f32_e32 v48, 0xbfb8aa3b, v174
	v_fmamk_f32 v32, v32, 0xbfb8aa3b, v49
	v_fmamk_f32 v16, v16, 0xbfb8aa3b, v48
	v_exp_f32_e32 v32, v32
	v_exp_f32_e32 v51, v16
	v_fmamk_f32 v17, v17, 0xbfb8aa3b, v48
	v_exp_f32_e32 v52, v17
	v_add_f32_e32 v32, 1.0, v32
	v_add_f32_e32 v51, 1.0, v51
	v_rcp_f32_e32 v17, v32
	v_rcp_f32_e32 v32, v51
	v_fmamk_f32 v33, v33, 0xbfb8aa3b, v49
	v_fmamk_f32 v34, v34, 0xbfb8aa3b, v49
	v_exp_f32_e32 v33, v33
	v_exp_f32_e32 v34, v34
	v_add_f32_e32 v33, 1.0, v33
	v_add_f32_e32 v34, 1.0, v34
	v_rcp_f32_e32 v33, v33
	v_rcp_f32_e32 v34, v34
	v_fmamk_f32 v18, v18, 0xbfb8aa3b, v48
	v_fmamk_f32 v19, v19, 0xbfb8aa3b, v48
	v_exp_f32_e32 v18, v18
	s_waitcnt lgkmcnt(0)
	v_mul_f32_e32 v50, 0x3fb8aa3b, v251
	v_mul_f32_e32 v16, v17, v50
	v_mul_f32_e32 v17, v33, v50
	v_exp_f32_e32 v33, v16
	v_mul_f32_e32 v16, v34, v50
	v_exp_f32_e32 v53, v16
	v_fmamk_f32 v16, v35, 0xbfb8aa3b, v49
	v_exp_f32_e32 v16, v16
	v_exp_f32_e32 v51, v17
	v_add_f32_e32 v16, 1.0, v16
	v_rcp_f32_e32 v16, v16
	v_exp_f32_e32 v19, v19
	v_add_f32_e32 v52, 1.0, v52
	v_add_f32_e32 v18, 1.0, v18
	v_mul_f32_e32 v16, v16, v50
	v_exp_f32_e32 v16, v16
	v_fma_f32 v35, -v53, v53, 1.0
	v_rcp_f32_e32 v17, v52
	v_fma_f32 v34, -v33, v33, 1.0
	v_fma_f32 v52, -v51, v51, 1.0
	v_rcp_f32_e32 v18, v18
	v_sqrt_f32_e32 v35, v35
	v_add_f32_e32 v19, 1.0, v19
	v_fma_f32 v54, -v16, v16, 1.0
	v_sqrt_f32_e32 v34, v34
	v_sqrt_f32_e32 v52, v52
	v_rcp_f32_e32 v19, v19
	v_sqrt_f32_e32 v54, v54
	v_mul_f32_e32 v35, v18, v35
	v_fmamk_f32 v18, v36, 0xbfb8aa3b, v49
	v_mul_f32_e32 v32, v32, v34
	v_mul_f32_e32 v34, v17, v52
	v_mul_f32_e32 v17, v19, v54
	v_fmamk_f32 v19, v20, 0xbfb8aa3b, v48
	v_exp_f32_e32 v18, v18
	v_exp_f32_e32 v19, v19
	v_mul_f32_e32 v3, v3, v17
	v_add_f32_e32 v17, 1.0, v18
	v_rcp_f32_e32 v17, v17
	v_add_f32_e32 v18, 1.0, v19
	v_fmamk_f32 v19, v37, 0xbfb8aa3b, v49
	v_exp_f32_e32 v19, v19
	v_mul_f32_e32 v17, v17, v50
	v_exp_f32_e32 v36, v17
	v_add_f32_e32 v17, 1.0, v19
	v_rcp_f32_e32 v17, v17
	v_fmamk_f32 v19, v21, 0xbfb8aa3b, v48
	v_exp_f32_e32 v19, v19
	v_mul_f32_e32 v17, v17, v50
	v_exp_f32_e32 v37, v17
	v_fmamk_f32 v17, v38, 0xbfb8aa3b, v49
	v_exp_f32_e32 v17, v17
	v_fmamk_f32 v23, v23, 0xbfb8aa3b, v48
	v_add_f32_e32 v19, 1.0, v19
	v_fma_f32 v21, -v37, v37, 1.0
	v_add_f32_e32 v17, 1.0, v17
	v_rcp_f32_e32 v17, v17
	v_fma_f32 v20, -v36, v36, 1.0
	v_rcp_f32_e32 v19, v19
	v_mul_f32_e32 v17, v17, v50
	v_exp_f32_e32 v38, v17
	v_fmamk_f32 v17, v39, 0xbfb8aa3b, v49
	v_exp_f32_e32 v17, v17
	v_sqrt_f32_e32 v21, v21
	v_exp_f32_e32 v23, v23
	v_rcp_f32_e32 v18, v18
	v_add_f32_e32 v17, 1.0, v17
	v_rcp_f32_e32 v17, v17
	v_sqrt_f32_e32 v20, v20
	v_add_f32_e32 v23, 1.0, v23
	v_mul_f32_e32 v55, v19, v21
	v_mul_f32_e32 v17, v17, v50
	v_exp_f32_e32 v17, v17
	v_fmamk_f32 v19, v40, 0xbfb8aa3b, v49
	v_rcp_f32_e32 v23, v23
	v_mul_f32_e32 v54, v18, v20
	v_fma_f32 v52, -v17, v17, 1.0
	v_sqrt_f32_e32 v52, v52
	v_fmamk_f32 v20, v24, 0xbfb8aa3b, v48
	v_fmamk_f32 v22, v22, 0xbfb8aa3b, v48
	v_exp_f32_e32 v19, v19
	v_exp_f32_e32 v20, v20
	v_exp_f32_e32 v22, v22
	v_mul_f32_e32 v18, v23, v52
	v_mul_f32_e32 v7, v7, v18
	v_add_f32_e32 v18, 1.0, v19
	v_rcp_f32_e32 v18, v18
	v_add_f32_e32 v19, 1.0, v20
	v_fmamk_f32 v20, v41, 0xbfb8aa3b, v49
	v_add_f32_e32 v22, 1.0, v22
	v_fma_f32 v39, -v38, v38, 1.0
	v_rcp_f32_e32 v22, v22
	v_sqrt_f32_e32 v39, v39
	v_exp_f32_e32 v20, v20
	v_mul_f32_e32 v18, v18, v50
	v_mul_f32_e32 v21, v22, v39
	v_exp_f32_e32 v39, v18
	v_add_f32_e32 v18, 1.0, v20
	v_rcp_f32_e32 v18, v18
	v_fmamk_f32 v20, v25, 0xbfb8aa3b, v48
	v_exp_f32_e32 v20, v20
	v_mul_f32_e32 v18, v18, v50
	v_exp_f32_e32 v40, v18
	v_fmamk_f32 v18, v42, 0xbfb8aa3b, v49
	v_exp_f32_e32 v18, v18
	v_fmamk_f32 v24, v26, 0xbfb8aa3b, v48
	v_fmamk_f32 v26, v27, 0xbfb8aa3b, v48
	v_add_f32_e32 v20, 1.0, v20
	v_add_f32_e32 v18, 1.0, v18
	v_rcp_f32_e32 v18, v18
	v_fma_f32 v23, -v40, v40, 1.0
	v_fma_f32 v22, -v39, v39, 1.0
	v_mul_f32_e32 v18, v18, v50
	v_exp_f32_e32 v41, v18
	v_fmamk_f32 v18, v43, 0xbfb8aa3b, v49
	v_exp_f32_e32 v18, v18
	v_rcp_f32_e32 v20, v20
	v_sqrt_f32_e32 v23, v23
	v_exp_f32_e32 v26, v26
	v_add_f32_e32 v18, 1.0, v18
	v_rcp_f32_e32 v18, v18
	v_rcp_f32_e32 v19, v19
	v_sqrt_f32_e32 v22, v22
	v_add_f32_e32 v26, 1.0, v26
	v_mul_f32_e32 v18, v18, v50
	v_exp_f32_e32 v18, v18
	v_mul_f32_e32 v43, v20, v23
	v_fmamk_f32 v20, v44, 0xbfb8aa3b, v49
	v_rcp_f32_e32 v26, v26
	v_fma_f32 v27, -v18, v18, 1.0
	v_sqrt_f32_e32 v27, v27
	v_mul_f32_e32 v42, v19, v22
	v_fmamk_f32 v22, v28, 0xbfb8aa3b, v48
	v_exp_f32_e32 v20, v20
	v_exp_f32_e32 v22, v22
	v_mul_f32_e32 v19, v26, v27
	v_mul_f32_e32 v11, v11, v19
	v_add_f32_e32 v19, 1.0, v20
	v_rcp_f32_e32 v19, v19
	v_add_f32_e32 v20, 1.0, v22
	v_fmamk_f32 v22, v45, 0xbfb8aa3b, v49
	v_exp_f32_e32 v22, v22
	v_mul_f32_e32 v19, v19, v50
	v_exp_f32_e32 v44, v19
	v_add_f32_e32 v19, 1.0, v22
	v_rcp_f32_e32 v19, v19
	v_exp_f32_e32 v24, v24
	v_fmamk_f32 v22, v29, 0xbfb8aa3b, v48
	v_mul_f32_e32 v19, v19, v50
	v_exp_f32_e32 v45, v19
	v_fmamk_f32 v19, v46, 0xbfb8aa3b, v49
	v_exp_f32_e32 v19, v19
	v_add_f32_e32 v24, 1.0, v24
	v_fma_f32 v25, -v41, v41, 1.0
	v_add_f32_e32 v19, 1.0, v19
	v_rcp_f32_e32 v19, v19
	v_exp_f32_e32 v22, v22
	v_rcp_f32_e32 v24, v24
	v_sqrt_f32_e32 v25, v25
	v_mul_f32_e32 v19, v19, v50
	v_exp_f32_e32 v46, v19
	v_fmamk_f32 v19, v47, 0xbfb8aa3b, v49
	v_add_f32_e32 v22, 1.0, v22
	v_exp_f32_e32 v19, v19
	v_mul_f32_e32 v52, v24, v25
	v_rcp_f32_e32 v24, v22
	v_fma_f32 v22, -v45, v45, 1.0
	v_sqrt_f32_e32 v25, v22
	v_fmamk_f32 v22, v30, 0xbfb8aa3b, v48
	v_exp_f32_e32 v22, v22
	v_add_f32_e32 v19, 1.0, v19
	v_rcp_f32_e32 v19, v19
	v_fma_f32 v27, -v46, v46, 1.0
	v_add_f32_e32 v22, 1.0, v22
	v_rcp_f32_e32 v26, v22
	v_fmamk_f32 v22, v31, 0xbfb8aa3b, v48
	v_mul_f32_e32 v19, v19, v50
	v_exp_f32_e32 v28, v22
	v_exp_f32_e32 v22, v19
	v_sqrt_f32_e32 v19, v27
	v_fma_f32 v23, -v44, v44, 1.0
	v_add_f32_e32 v27, 1.0, v28
	v_fma_f32 v28, -v22, v22, 1.0
	v_rcp_f32_e32 v27, v27
	v_sqrt_f32_e32 v28, v28
	v_rcp_f32_e32 v20, v20
	v_sqrt_f32_e32 v23, v23
	v_mul_f32_e32 v49, v26, v19
	v_mul_f32_e32 v19, v27, v28
	v_fmac_f32_e32 v7, 0, v17
	v_mul_f32_e32 v15, v15, v19
	v_mul_f32_e32 v19, v38, v7
	v_fmac_f32_e32 v19, v6, v21
	v_fmac_f32_e32 v3, 0, v16
	v_mul_f32_e32 v21, v37, v19
	v_mul_f32_e32 v47, v20, v23
	v_mul_f32_e32 v20, v53, v3
	v_fmac_f32_e32 v21, v5, v55
	v_fmac_f32_e32 v15, 0, v22
	v_mul_f32_e32 v48, v24, v25
	v_fmac_f32_e32 v20, v2, v35
	v_mul_f32_e32 v24, v36, v21
	v_fmac_f32_e32 v11, 0, v18
	v_mul_f32_e32 v2, v46, v15
	v_fmac_f32_e32 v24, v4, v54
	v_mul_f32_e32 v4, v41, v11
	v_fmac_f32_e32 v2, v14, v49
	v_fmac_f32_e32 v4, v10, v52
	v_mul_f32_e32 v5, v45, v2
	v_mul_f32_e32 v23, v51, v20
	v_mul_f32_e32 v6, v40, v4
	v_fmac_f32_e32 v5, v13, v48
	v_fmac_f32_e32 v23, v1, v34
	v_fmac_f32_e32 v6, v9, v43
	v_mul_f32_e32 v14, v22, v46
	v_mul_f32_e32 v9, v44, v5
	v_mul_f32_e32 v25, v33, v23
	v_mul_f32_e32 v13, v45, v14
	v_fmac_f32_e32 v9, v12, v47
	v_fmac_f32_e32 v25, v0, v32
	v_mul_f32_e32 v12, v44, v13
	ds_bpermute_b32 v0, v137, v9
	ds_bpermute_b32 v35, v137, v12
	v_mul_f32_e32 v28, v18, v41
	v_mul_f32_e32 v26, v16, v53
	v_mul_f32_e32 v27, v17, v38
	v_mul_f32_e32 v31, v40, v28
	v_mul_f32_e32 v10, v39, v6
	v_mul_f32_e32 v29, v51, v26
	v_mul_f32_e32 v30, v37, v27
	v_fmac_f32_e32 v10, v8, v42
	v_mul_f32_e32 v34, v39, v31
	v_mul_f32_e32 v32, v33, v29
	v_mul_f32_e32 v33, v36, v30
	s_waitcnt lgkmcnt(1)
	v_cndmask_b32_e64 v36, v0, v9, s[4:5]
	v_cndmask_b32_e64 v37, v9, v0, s[4:5]
	ds_bpermute_b32 v0, v137, v34
	ds_bpermute_b32 v40, v137, v10
	s_waitcnt lgkmcnt(2)
	v_cndmask_b32_e64 v8, v12, v35, s[4:5]
	v_fmac_f32_e32 v37, 0, v8
	ds_bpermute_b32 v8, v137, v33
	v_cndmask_b32_e64 v1, v35, v12, s[4:5]
	v_mul_f32_e32 v38, v12, v35
	v_fmac_f32_e32 v36, v1, v37
	s_waitcnt lgkmcnt(2)
	v_cndmask_b32_e64 v1, v0, v34, s[4:5]
	s_waitcnt lgkmcnt(1)
	v_cndmask_b32_e64 v39, v40, v10, s[4:5]
	v_cndmask_b32_e64 v0, v34, v0, s[4:5]
	v_cndmask_b32_e64 v40, v10, v40, s[4:5]
	ds_bpermute_b32 v44, v137, v24
	v_mul_f32_e32 v41, v38, v0
	v_fmac_f32_e32 v40, v0, v36
	v_mul_f32_e32 v42, v1, v41
	v_fmac_f32_e32 v39, v1, v40
	s_waitcnt lgkmcnt(1)
	v_cndmask_b32_e64 v0, v8, v33, s[4:5]
	v_cndmask_b32_e64 v1, v33, v8, s[4:5]
	ds_bpermute_b32 v8, v137, v32
	ds_bpermute_b32 v47, v137, v25
	s_waitcnt lgkmcnt(2)
	v_cndmask_b32_e64 v43, v44, v24, s[4:5]
	v_cndmask_b32_e64 v44, v24, v44, s[4:5]
	v_mul_f32_e32 v45, v1, v42
	v_fmac_f32_e32 v44, v1, v39
	v_mul_f32_e32 v46, v0, v45
	v_fmac_f32_e32 v43, v0, v44
	s_waitcnt lgkmcnt(1)
	v_cndmask_b32_e64 v0, v32, v8, s[4:5]
	s_waitcnt lgkmcnt(0)
	v_cndmask_b32_e64 v47, v25, v47, s[4:5]
	v_mul_f32_e32 v48, v0, v46
	v_fmac_f32_e32 v47, v0, v43
	s_and_saveexec_b64 s[12:13], s[4:5]
	v_mul_f32_e32 v0, v32, v48
	v_fma_f32 v1, v32, v47, v25
	ds_write_b64 v136, v[0:1] offset:6144
	s_or_b64 exec, exec, s[12:13]
	s_and_b64 vcc, exec, s[8:9]
	s_waitcnt lgkmcnt(0)
	s_barrier
	s_cbranch_vccnz .LBB0_293
	v_add3_u32 v49, v140, v91, s95
	v_mov_b32_e32 v8, 1.0
	v_mov_b32_e32 v1, 0
	s_mov_b32 s8, 7

.LBB0_331:
	ds_read_b128 v[178:181], v148 offset:24576
	ds_read_b128 v[182:185], v148 offset:57344
	ds_read_b128 v[186:189], v150 offset:24576
	ds_read_b128 v[190:193], v150 offset:57344
	ds_read_b128 v[194:197], v145 offset:24576
	ds_read_b128 v[198:201], v145 offset:57344
	ds_read_b128 v[202:205], v149 offset:24576
	ds_read_b128 v[206:209], v149 offset:57344
	ds_read_b128 v[210:213], v144 offset:24576
	ds_read_b128 v[214:217], v144 offset:57344
	ds_read_b128 v[218:221], v147 offset:24576
	ds_read_b128 v[222:225], v147 offset:57344
	ds_read_b128 v[226:229], v143 offset:24576
	ds_read_b128 v[230:233], v143 offset:57344
	ds_read_b128 v[234:237], v146 offset:24576
	ds_read_b128 v[238:241], v146 offset:57344
	v_lshl_add_u64 v[126:127], s[36:37], 0, v[88:89]
	v_lshl_add_u64 v[128:129], s[40:41], 0, v[88:89]
	v_lshl_add_u64 v[130:131], s[42:43], 0, v[88:89]
	v_cndmask_b32_e64 v1, v13, 1.0, s[0:1]
	v_cndmask_b32_e64 v2, v10, 0, s[0:1]
	v_cndmask_b32_e64 v10, v42, v15, s[0:1]
	v_cndmask_b32_e64 v13, v17, v14, s[0:1]
	v_cndmask_b32_e64 v14, v46, v43, s[0:1]
	v_cndmask_b32_e64 v15, v44, v41, s[0:1]
	s_ashr_i32 s9, s8, 31
	v_lshlrev_b32_e32 v88, 2, v94
	v_cndmask_b32_e64 v17, v96, v47, s[0:1]
	v_cndmask_b32_e64 v41, v91, v45, s[0:1]
	v_fmac_f32_e32 v18, v32, v2
	v_mul_f32_e32 v32, v1, v32
	v_fmac_f32_e32 v31, v33, v2
	v_mul_f32_e32 v33, v1, v33
	v_fmac_f32_e32 v30, v34, v2
	v_mul_f32_e32 v34, v1, v34
	v_fmac_f32_e32 v29, v35, v2
	v_mul_f32_e32 v1, v1, v35
	v_fmac_f32_e32 v19, v20, v13
	v_mul_f32_e32 v2, v20, v10
	v_fmac_f32_e32 v28, v36, v13
	v_mul_f32_e32 v20, v36, v10
	v_fmac_f32_e32 v27, v37, v13
	v_mul_f32_e32 v35, v37, v10
	v_fmac_f32_e32 v26, v38, v13
	v_mul_f32_e32 v10, v38, v10
	v_fmac_f32_e32 v23, v12, v15
	v_mul_f32_e32 v38, v12, v14
	v_lshl_add_u64 v[12:13], s[22:23], 0, v[88:89]
	s_lshl_b64 s[4:5], s[8:9], 12
	v_fmac_f32_e32 v24, v40, v15
	v_mul_f32_e32 v37, v40, v14
	v_fmac_f32_e32 v7, v4, v41
	v_mul_f32_e32 v40, v4, v17
	v_lshl_add_u64 v[94:95], v[12:13], 0, s[4:5]
	v_lshlrev_b32_e32 v12, 14, v93
	v_mul_f32_e32 v4, v32, v0
	v_mov_b32_e32 v13, v89
	v_fmac_f32_e32 v18, v32, v3
	v_cvt_pk_bf16_f32 v4, v18, v4
	v_lshl_add_u64 v[96:97], v[94:95], 0, v[12:13]
	global_load_dword v172, v[130:131], off offset:128
	global_load_dword v173, v[126:127], off offset:128
	global_load_dword v174, v[128:129], off offset:128
	global_store_dword v[96:97], v4, off nt
	v_mul_f32_e32 v4, v33, v0
	v_or_b32_e32 v88, 0x1000, v12
	v_fmac_f32_e32 v21, v22, v15
	v_mul_f32_e32 v22, v22, v14
	v_fmac_f32_e32 v25, v39, v15
	v_mul_f32_e32 v36, v39, v14
	v_fmac_f32_e32 v31, v33, v3
	v_cvt_pk_bf16_f32 v4, v31, v4
	v_lshl_add_u64 v[14:15], v[94:95], 0, v[88:89]
	v_or_b32_e32 v98, 0x2000, v12
	v_mov_b32_e32 v99, v89
	global_store_dword v[14:15], v4, off nt
	v_mul_f32_e32 v4, v34, v0
	v_lshl_add_u64 v[14:15], v[94:95], 0, v[98:99]
	v_fmac_f32_e32 v29, v1, v3
	v_mul_f32_e32 v1, v1, v0
	v_or_b32_e32 v100, 0x3000, v12
	v_mov_b32_e32 v101, v89
	v_fmac_f32_e32 v30, v34, v3
	v_cvt_pk_bf16_f32 v4, v30, v4
	global_store_dword v[14:15], v4, off nt
	v_cvt_pk_bf16_f32 v1, v29, v1
	v_lshl_add_u64 v[14:15], v[94:95], 0, v[100:101]
	global_store_dword v[14:15], v1, off nt
	v_mul_f32_e32 v1, v2, v0
	v_or_b32_e32 v102, 0x8000, v12
	v_mov_b32_e32 v103, v89
	v_fmac_f32_e32 v19, v2, v3
	v_cvt_pk_bf16_f32 v1, v19, v1
	v_lshl_add_u64 v[14:15], v[94:95], 0, v[102:103]
	global_store_dword v[14:15], v1, off nt
	v_mul_f32_e32 v1, v20, v0
	v_or_b32_e32 v104, 0x9000, v12
	v_mov_b32_e32 v105, v89
	v_fmac_f32_e32 v28, v20, v3
	v_cvt_pk_bf16_f32 v1, v28, v1
	v_lshl_add_u64 v[14:15], v[94:95], 0, v[104:105]
	global_store_dword v[14:15], v1, off nt
	v_mul_f32_e32 v1, v35, v0
	v_or_b32_e32 v106, 0xa000, v12
	v_mov_b32_e32 v107, v89
	v_fmac_f32_e32 v27, v35, v3
	v_cvt_pk_bf16_f32 v1, v27, v1
	v_lshl_add_u64 v[14:15], v[94:95], 0, v[106:107]
	global_store_dword v[14:15], v1, off nt
	v_mul_f32_e32 v1, v10, v0
	v_or_b32_e32 v108, 0xb000, v12
	v_mov_b32_e32 v109, v89
	v_fmac_f32_e32 v26, v10, v3
	v_cvt_pk_bf16_f32 v1, v26, v1
	v_lshl_add_u64 v[14:15], v[94:95], 0, v[108:109]
	global_store_dword v[14:15], v1, off nt
	v_mul_f32_e32 v1, v22, v0
	v_or_b32_e32 v110, 0x10000, v12
	v_mov_b32_e32 v111, v89
	v_fmac_f32_e32 v21, v22, v3
	v_cvt_pk_bf16_f32 v1, v21, v1
	v_lshl_add_u64 v[14:15], v[94:95], 0, v[110:111]
	global_store_dword v[14:15], v1, off nt
	v_mul_f32_e32 v1, v36, v0
	v_or_b32_e32 v112, 0x11000, v12
	v_mov_b32_e32 v113, v89
	v_fmac_f32_e32 v25, v36, v3
	v_cvt_pk_bf16_f32 v1, v25, v1
	v_lshl_add_u64 v[14:15], v[94:95], 0, v[112:113]
	global_store_dword v[14:15], v1, off nt
	v_mul_f32_e32 v1, v37, v0
	v_or_b32_e32 v114, 0x12000, v12
	v_mov_b32_e32 v115, v89
	v_fmac_f32_e32 v24, v37, v3
	v_cvt_pk_bf16_f32 v1, v24, v1
	v_lshl_add_u64 v[14:15], v[94:95], 0, v[114:115]
	global_store_dword v[14:15], v1, off nt
	v_mul_f32_e32 v1, v38, v0
	v_or_b32_e32 v116, 0x13000, v12
	v_mov_b32_e32 v117, v89
	v_fmac_f32_e32 v8, v16, v41
	v_mul_f32_e32 v16, v16, v17
	v_fmac_f32_e32 v23, v38, v3
	v_cvt_pk_bf16_f32 v1, v23, v1
	v_lshl_add_u64 v[14:15], v[94:95], 0, v[116:117]
	global_store_dword v[14:15], v1, off nt
	v_fmac_f32_e32 v8, v16, v3
	v_mul_f32_e32 v1, v16, v0
	v_or_b32_e32 v118, 0x18000, v12
	v_mov_b32_e32 v119, v89
	v_fmac_f32_e32 v5, v9, v41
	v_mul_f32_e32 v39, v9, v17
	v_cvt_pk_bf16_f32 v1, v8, v1
	v_lshl_add_u64 v[8:9], v[94:95], 0, v[118:119]
	global_store_dword v[8:9], v1, off nt
	v_fmac_f32_e32 v5, v39, v3
	v_mul_f32_e32 v1, v39, v0
	v_or_b32_e32 v120, 0x19000, v12
	v_mov_b32_e32 v121, v89
	v_cvt_pk_bf16_f32 v1, v5, v1
	v_lshl_add_u64 v[4:5], v[94:95], 0, v[120:121]
	v_fmac_f32_e32 v11, v6, v41
	v_mul_f32_e32 v6, v6, v17
	s_lshl_b32 s6, s63, 11
	global_store_dword v[4:5], v1, off nt
	v_mul_f32_e32 v1, v40, v0
	v_or_b32_e32 v122, 0x1a000, v12
	v_mov_b32_e32 v123, v89
	s_or_b32 s6, s6, s70
	v_fmac_f32_e32 v7, v40, v3
	v_cvt_pk_bf16_f32 v1, v7, v1
	v_lshl_add_u64 v[4:5], v[94:95], 0, v[122:123]
	v_mul_f32_e32 v0, v6, v0
	v_or_b32_e32 v124, 0x1b000, v12
	v_mov_b32_e32 v125, v89
	v_lshl_add_u32 v142, v92, 3, 16
	v_cmp_gt_i32_e64 s[4:5], 32, v92
	v_add_u32_e32 v92, s6, v92
	global_store_dword v[4:5], v1, off nt
	v_fmac_f32_e32 v11, v6, v3
	v_cvt_pk_bf16_f32 v2, v11, v0
	v_lshl_add_u64 v[0:1], v[94:95], 0, v[124:125]
	global_store_dword v[0:1], v2, off nt
	s_and_saveexec_b64 s[6:7], s[4:5]
	s_cbranch_execz .LBB0_333
	ds_read2_b64 v[0:3], v142 offset1:32
	ds_read2_b64 v[4:7], v142 offset0:64 offset1:96
	ds_read2_b64 v[8:11], v142 offset0:128 offset1:160
	ds_read2_b64 v[12:15], v142 offset0:192 offset1:224
	v_ashrrev_i32_e32 v93, 31, v92
	s_waitcnt lgkmcnt(3)
	v_fma_f32 v16, 0, v0, v1
	v_pk_mul_f32 v[0:1], v[0:1], v[2:3]
	v_fma_f32 v2, v2, v16, v3
	s_waitcnt lgkmcnt(2)
	v_fma_f32 v2, v4, v2, v5
	v_fma_f32 v2, v6, v2, v7
	s_waitcnt lgkmcnt(1)
	v_fma_f32 v3, v8, v2, v9
	v_mov_b32_e32 v2, v0
	v_mov_b32_e32 v16, v4
	v_mov_b32_e32 v17, v10
	v_pk_mul_f32 v[0:1], v[0:1], v[4:5]
	v_pk_fma_f32 v[2:3], v[2:3], v[16:17], v[10:11]
	v_pk_mul_f32 v[0:1], v[0:1], v[6:7]
	s_waitcnt lgkmcnt(0)
	v_mov_b32_e32 v9, v12
	v_mov_b32_e32 v1, v3
	v_pk_mul_f32 v[2:3], v[0:1], v[8:9]
	v_pk_fma_f32 v[0:1], v[0:1], v[8:9], v[12:13]
	v_pk_mul_f32 v[2:3], v[2:3], v[10:11]
	v_mov_b32_e32 v4, v12
	v_mov_b32_e32 v0, v2
	v_mov_b32_e32 v5, v14
	v_pk_mul_f32 v[2:3], v[2:3], v[12:13]
	v_pk_fma_f32 v[0:1], v[0:1], v[4:5], v[14:15]
	v_pk_mul_f32 v[2:3], v[2:3], v[14:15]
	s_nop 0
	v_mov_b32_e32 v3, v1
	v_lshl_add_u64 v[0:1], v[92:93], 3, s[24:25]
	global_store_dwordx2 v[0:1], v[2:3], off
.LBB0_333:
	s_or_b64 exec, exec, s[6:7]
	s_setprio 1
	s_waitcnt lgkmcnt(0)
	v_mfma_f32_32x32x16_bf16 v[32:47], v[48:51], v[178:181], 0
	v_mfma_f32_32x32x16_bf16 v[16:31], v[48:51], v[182:185], 0
	v_mfma_f32_32x32x16_bf16 v[32:47], v[52:55], v[186:189], v[32:47]
	v_mfma_f32_32x32x16_bf16 v[16:31], v[52:55], v[190:193], v[16:31]
	v_mfma_f32_32x32x16_bf16 v[32:47], v[56:59], v[194:197], v[32:47]
	v_mfma_f32_32x32x16_bf16 v[16:31], v[56:59], v[198:201], v[16:31]
	v_mfma_f32_32x32x16_bf16 v[32:47], v[60:63], v[202:205], v[32:47]
	v_mfma_f32_32x32x16_bf16 v[16:31], v[60:63], v[206:209], v[16:31]
	v_mfma_f32_32x32x16_bf16 v[32:47], v[64:67], v[210:213], v[32:47]
	v_mfma_f32_32x32x16_bf16 v[16:31], v[64:67], v[214:217], v[16:31]
	v_mfma_f32_32x32x16_bf16 v[32:47], v[68:71], v[218:221], v[32:47]
	v_mfma_f32_32x32x16_bf16 v[16:31], v[68:71], v[222:225], v[16:31]
	v_mfma_f32_32x32x16_bf16 v[32:47], v[72:75], v[226:229], v[32:47]
	v_mfma_f32_32x32x16_bf16 v[16:31], v[72:75], v[230:233], v[16:31]
	v_mfma_f32_32x32x16_bf16 v[32:47], v[76:79], v[234:237], v[32:47]
	v_mfma_f32_32x32x16_bf16 v[16:31], v[76:79], v[238:241], v[16:31]
	v_mfma_f32_32x32x16_bf16 v[0:15], v[56:59], v[80:83], 0
	v_mfma_f32_32x32x16_bf16 v[0:15], v[60:63], v[84:87], v[0:15]
	s_setprio 0
	s_waitcnt vmcnt(16)
	ds_read_b32 v251, v167 offset:128
	v_mul_f32_e32 v151, 0xbfb8aa3b, v173
	v_mul_f32_e32 v93, 0xbfb8aa3b, v174
	v_fmamk_f32 v32, v32, 0xbfb8aa3b, v151
	v_fmamk_f32 v34, v34, 0xbfb8aa3b, v151
	v_fmamk_f32 v33, v33, 0xbfb8aa3b, v151
	v_fmamk_f32 v35, v35, 0xbfb8aa3b, v151
	v_fmamk_f32 v16, v16, 0xbfb8aa3b, v93
	v_fmamk_f32 v17, v17, 0xbfb8aa3b, v93
	v_exp_f32_e32 v32, v32
	v_exp_f32_e32 v34, v34
	v_exp_f32_e32 v33, v33
	v_exp_f32_e32 v161, v35
	v_exp_f32_e32 v91, v16
	v_exp_f32_e32 v152, v17
	v_add_f32_e32 v32, 1.0, v32
	v_add_f32_e32 v162, 1.0, v34
	v_add_f32_e32 v33, 1.0, v33
	v_rcp_f32_e32 v163, v32
	v_rcp_f32_e32 v165, v33
	v_add_f32_e32 v91, 1.0, v91
	v_rcp_f32_e32 v164, v91
	v_add_f32_e32 v152, 1.0, v152
	v_rcp_f32_e32 v166, v152
	v_fmamk_f32 v18, v18, 0xbfb8aa3b, v93
	v_exp_f32_e32 v18, v18
	v_fmamk_f32 v20, v20, 0xbfb8aa3b, v93
	v_add_f32_e32 v18, 1.0, v18
	v_exp_f32_e32 v20, v20
	v_fmamk_f32 v19, v19, 0xbfb8aa3b, v93
	v_exp_f32_e32 v19, v19
	v_fmamk_f32 v21, v21, 0xbfb8aa3b, v93
	s_waitcnt lgkmcnt(0)
	v_mul_f32_e32 v33, 0x3fb8aa3b, v251
	v_mul_f32_e32 v16, v163, v33
	v_exp_f32_e32 v32, v16
	v_mul_f32_e32 v17, v165, v33
	v_exp_f32_e32 v34, v17
	v_rcp_f32_e32 v16, v162
	v_rcp_f32_e32 v17, v18
	v_fma_f32 v18, -v32, v32, 1.0
	v_sqrt_f32_e32 v18, v18
	v_mul_f32_e32 v16, v16, v33
	v_add_f32_e32 v19, 1.0, v19
	v_mul_f32_e32 v18, v164, v18
	v_mul_f32_e32 v18, v0, v18
	v_exp_f32_e32 v0, v16
	v_add_f32_e32 v16, 1.0, v161
	v_rcp_f32_e32 v16, v16
	v_rcp_f32_e32 v19, v19
	v_fma_f32 v91, -v0, v0, 1.0
	v_sqrt_f32_e32 v91, v91
	v_mul_f32_e32 v16, v16, v33
	v_exp_f32_e32 v152, v16
	v_fmamk_f32 v16, v36, 0xbfb8aa3b, v151
	v_exp_f32_e32 v16, v16
	v_mul_f32_e32 v91, v17, v91
	v_add_f32_e32 v17, 1.0, v20
	v_fma_f32 v36, -v152, v152, 1.0
	v_add_f32_e32 v16, 1.0, v16
	v_rcp_f32_e32 v16, v16
	v_sqrt_f32_e32 v36, v36
	v_rcp_f32_e32 v17, v17
	v_mul_f32_e32 v16, v16, v33
	v_exp_f32_e32 v20, v16
	v_fmamk_f32 v16, v37, 0xbfb8aa3b, v151
	v_exp_f32_e32 v16, v16
	v_mul_f32_e32 v36, v19, v36
	v_fma_f32 v19, -v20, v20, 1.0
	v_sqrt_f32_e32 v19, v19
	v_add_f32_e32 v16, 1.0, v16
	v_rcp_f32_e32 v16, v16
	v_exp_f32_e32 v21, v21
	v_mul_f32_e32 v17, v17, v19
	v_mul_f32_e32 v19, v4, v17
	v_mul_f32_e32 v16, v16, v33
	v_exp_f32_e32 v37, v16
	v_fmamk_f32 v16, v38, 0xbfb8aa3b, v151
	v_exp_f32_e32 v16, v16
	v_add_f32_e32 v4, 1.0, v21
	v_fmamk_f32 v21, v22, 0xbfb8aa3b, v93
	v_add_f32_e32 v16, 1.0, v16
	v_rcp_f32_e32 v16, v16
	v_fma_f32 v17, -v37, v37, 1.0
	v_exp_f32_e32 v21, v21
	v_rcp_f32_e32 v4, v4
	v_mul_f32_e32 v16, v16, v33
	v_sqrt_f32_e32 v17, v17
	v_exp_f32_e32 v38, v16
	v_add_f32_e32 v16, 1.0, v21
	v_fmamk_f32 v21, v39, 0xbfb8aa3b, v151
	v_mul_f32_e32 v4, v4, v17
	v_fma_f32 v17, -v38, v38, 1.0
	v_rcp_f32_e32 v16, v16
	v_sqrt_f32_e32 v17, v17
	v_exp_f32_e32 v21, v21
	v_fmamk_f32 v22, v23, 0xbfb8aa3b, v93
	v_mul_f32_e32 v23, v16, v17
	v_add_f32_e32 v16, 1.0, v21
	v_rcp_f32_e32 v16, v16
	v_fmamk_f32 v21, v40, 0xbfb8aa3b, v151
	v_exp_f32_e32 v21, v21
	v_mul_f32_e32 v16, v16, v33
	v_exp_f32_e32 v39, v16
	v_add_f32_e32 v16, 1.0, v21
	v_rcp_f32_e32 v16, v16
	v_exp_f32_e32 v22, v22
	v_fmamk_f32 v21, v24, 0xbfb8aa3b, v93
	v_mul_f32_e32 v16, v16, v33
	v_add_f32_e32 v17, 1.0, v22
	v_fma_f32 v22, -v39, v39, 1.0
	v_sqrt_f32_e32 v24, v22
	v_exp_f32_e32 v22, v16
	v_fmamk_f32 v16, v41, 0xbfb8aa3b, v151
	v_exp_f32_e32 v16, v16
	v_exp_f32_e32 v21, v21
	v_fma_f32 v40, -v22, v22, 1.0
	v_rcp_f32_e32 v17, v17
	v_add_f32_e32 v16, 1.0, v16
	v_rcp_f32_e32 v16, v16
	v_add_f32_e32 v21, 1.0, v21
	v_rcp_f32_e32 v21, v21
	v_sqrt_f32_e32 v40, v40
	v_mul_f32_e32 v16, v16, v33
	v_mul_f32_e32 v24, v17, v24
	v_mul_f32_e32 v17, v21, v40
	v_exp_f32_e32 v40, v16
	v_fmamk_f32 v16, v42, 0xbfb8aa3b, v151
	v_fmamk_f32 v25, v25, 0xbfb8aa3b, v93
	v_exp_f32_e32 v16, v16
	v_exp_f32_e32 v25, v25
	v_fma_f32 v35, -v34, v34, 1.0
	v_sqrt_f32_e32 v35, v35
	v_add_f32_e32 v16, 1.0, v16
	v_add_f32_e32 v21, 1.0, v25
	v_rcp_f32_e32 v16, v16
	v_rcp_f32_e32 v25, v21
	v_fma_f32 v21, -v40, v40, 1.0
	v_sqrt_f32_e32 v41, v21
	v_fmamk_f32 v21, v26, 0xbfb8aa3b, v93
	v_mul_f32_e32 v16, v16, v33
	v_exp_f32_e32 v26, v21
	v_mul_f32_e32 v21, v8, v17
	v_mul_f32_e32 v8, v25, v41
	v_exp_f32_e32 v41, v16
	v_fmamk_f32 v16, v43, 0xbfb8aa3b, v151
	v_exp_f32_e32 v16, v16
	v_add_f32_e32 v17, 1.0, v26
	v_fma_f32 v25, -v41, v41, 1.0
	v_fmamk_f32 v26, v27, 0xbfb8aa3b, v93
	v_add_f32_e32 v16, 1.0, v16
	v_rcp_f32_e32 v16, v16
	v_rcp_f32_e32 v17, v17
	v_sqrt_f32_e32 v25, v25
	v_mul_f32_e32 v16, v16, v33
	v_exp_f32_e32 v26, v26
	v_exp_f32_e32 v153, v16
	v_mul_f32_e32 v154, v17, v25
	v_fmamk_f32 v25, v44, 0xbfb8aa3b, v151
	v_add_f32_e32 v16, 1.0, v26
	v_fmamk_f32 v26, v28, 0xbfb8aa3b, v93
	v_fma_f32 v17, -v153, v153, 1.0
	v_exp_f32_e32 v25, v25
	v_rcp_f32_e32 v16, v16
	v_sqrt_f32_e32 v17, v17
	v_exp_f32_e32 v26, v26
	v_add_f32_e32 v25, 1.0, v25
	v_rcp_f32_e32 v25, v25
	v_mul_f32_e32 v155, v16, v17
	v_add_f32_e32 v16, 1.0, v26
	v_fmamk_f32 v26, v29, 0xbfb8aa3b, v93
	v_exp_f32_e32 v26, v26
	v_rcp_f32_e32 v17, v16
	v_mul_f32_e32 v16, v25, v33
	v_fmamk_f32 v25, v45, 0xbfb8aa3b, v151
	v_exp_f32_e32 v25, v25
	v_add_f32_e32 v26, 1.0, v26
	v_rcp_f32_e32 v42, v26
	v_fmamk_f32 v26, v46, 0xbfb8aa3b, v151
	v_exp_f32_e32 v26, v26
	v_add_f32_e32 v25, 1.0, v25
	v_rcp_f32_e32 v25, v25
	v_fmamk_f32 v27, v30, 0xbfb8aa3b, v93
	v_exp_f32_e32 v27, v27
	v_add_f32_e32 v26, 1.0, v26
	v_rcp_f32_e32 v26, v26
	v_mul_f32_e32 v25, v25, v33
	v_exp_f32_e32 v43, v25
	v_add_f32_e32 v25, 1.0, v27
	v_rcp_f32_e32 v44, v25
	v_mul_f32_e32 v25, v26, v33
	v_fmamk_f32 v26, v47, 0xbfb8aa3b, v151
	v_exp_f32_e32 v26, v26
	v_fmamk_f32 v27, v31, 0xbfb8aa3b, v93
	v_exp_f32_e32 v27, v27
	v_add_f32_e32 v26, 1.0, v26
	v_rcp_f32_e32 v26, v26
	v_exp_f32_e32 v16, v16
	v_fmac_f32_e32 v18, 0, v32
	v_mul_f32_e32 v35, v166, v35
	v_exp_f32_e32 v45, v25
	v_add_f32_e32 v25, 1.0, v27
	v_mul_f32_e32 v31, v34, v18
	v_rcp_f32_e32 v46, v25
	v_mul_f32_e32 v25, v26, v33
	v_fmac_f32_e32 v31, v1, v35
	v_mul_f32_e32 v33, v32, v34
	v_fmac_f32_e32 v19, 0, v20
	v_mul_f32_e32 v30, v0, v31
	v_mul_f32_e32 v34, v0, v33
	v_mul_f32_e32 v28, v37, v19
	v_fma_f32 v0, -v16, v16, 1.0
	v_fmac_f32_e32 v28, v5, v4
	v_sqrt_f32_e32 v1, v0
	v_mul_f32_e32 v27, v38, v28
	v_fmac_f32_e32 v30, v2, v91
	v_fmac_f32_e32 v27, v6, v23
	v_fma_f32 v2, -v43, v43, 1.0
	v_mul_f32_e32 v26, v39, v27
	v_mov_b32_e32 v0, v89
	v_sqrt_f32_e32 v2, v2
	v_fmac_f32_e32 v26, v7, v24
	v_pk_mul_f32 v[6:7], v[16:17], v[0:1]
	v_mul_f32_e32 v29, v152, v30
	v_fmac_f32_e32 v6, v12, v7
	v_fmac_f32_e32 v29, v3, v36
	v_mov_b32_e32 v3, v6
	v_pk_mul_f32 v[4:5], v[42:43], v[2:3]
	v_fma_f32 v0, -v45, v45, 1.0
	v_exp_f32_e32 v47, v25
	v_fmac_f32_e32 v5, v13, v4
	v_sqrt_f32_e32 v4, v0
	v_fmac_f32_e32 v21, 0, v22
	v_mul_f32_e32 v25, v40, v21
	v_fmac_f32_e32 v25, v9, v8
	v_pk_mul_f32 v[8:9], v[44:45], v[4:5]
	v_fma_f32 v0, -v47, v47, 1.0
	v_fmac_f32_e32 v9, v14, v8
	v_sqrt_f32_e32 v8, v0
	ds_bpermute_b32 v0, v140, v29
	v_mul_f32_e32 v24, v41, v25
	v_mul_f32_e32 v35, v152, v34
	v_mul_f32_e32 v36, v20, v37
	v_fmac_f32_e32 v24, v10, v154
	v_mul_f32_e32 v37, v38, v36
	v_mul_f32_e32 v23, v153, v24
	ds_bpermute_b32 v13, v140, v35
	v_mul_f32_e32 v38, v39, v37
	v_fmac_f32_e32 v23, v11, v155
	v_pk_mul_f32 v[10:11], v[46:47], v[8:9]
	s_waitcnt lgkmcnt(1)
	v_cndmask_b32_e64 v14, v29, v0, s[0:1]
	v_fmac_f32_e32 v11, v15, v10
	v_cndmask_b32_e64 v10, v0, v29, s[0:1]
	ds_bpermute_b32 v0, v140, v38
	ds_bpermute_b32 v3, v140, v26
	v_mul_f32_e32 v39, v22, v40
	v_mul_f32_e32 v40, v41, v39
	s_waitcnt lgkmcnt(2)
	v_cndmask_b32_e64 v1, v13, v35, s[0:1]
	v_mul_f32_e32 v12, v153, v40
	v_mul_f32_e32 v7, v16, v43
	v_cndmask_b32_e64 v2, v35, v13, s[0:1]
	v_fmac_f32_e32 v10, 0, v1
	v_mul_f32_e32 v4, v45, v7
	v_mul_f32_e32 v15, v35, v13
	v_fmac_f32_e32 v14, v2, v10
	s_waitcnt lgkmcnt(1)
	v_cndmask_b32_e64 v1, v0, v38, s[0:1]
	s_waitcnt lgkmcnt(0)
	v_cndmask_b32_e64 v17, v3, v26, s[0:1]
	v_cndmask_b32_e64 v41, v26, v3, s[0:1]
	ds_bpermute_b32 v2, v140, v12
	ds_bpermute_b32 v3, v140, v23
	v_mul_f32_e32 v8, v47, v4
	v_cndmask_b32_e64 v0, v38, v0, s[0:1]
	v_mul_f32_e32 v42, v15, v1
	v_fmac_f32_e32 v17, v1, v14
	v_mul_f32_e32 v43, v0, v42
	v_fmac_f32_e32 v41, v0, v17
	ds_bpermute_b32 v1, v140, v8
	ds_bpermute_b32 v0, v140, v11
	s_waitcnt lgkmcnt(3)
	v_cndmask_b32_e64 v47, v2, v12, s[0:1]
	s_waitcnt lgkmcnt(2)
	v_cndmask_b32_e64 v44, v3, v23, s[0:1]
	v_cndmask_b32_e64 v2, v12, v2, s[0:1]
	v_cndmask_b32_e64 v45, v23, v3, s[0:1]
	v_mul_f32_e32 v46, v47, v43
	v_fmac_f32_e32 v44, v47, v41
	v_mul_f32_e32 v47, v2, v46
	v_fmac_f32_e32 v45, v2, v44
	s_waitcnt lgkmcnt(1)
	v_cndmask_b32_e64 v2, v1, v8, s[0:1]
	s_waitcnt lgkmcnt(0)
	v_cndmask_b32_e64 v91, v0, v11, s[0:1]
	v_mul_f32_e32 v93, v2, v47
	v_fmac_f32_e32 v91, v2, v45
	s_and_saveexec_b64 s[6:7], s[0:1]
	v_mul_f32_e32 v3, v91, v1
	v_mul_f32_e32 v2, v93, v1
	v_add_f32_e32 v3, v3, v0
	ds_write_b64 v139, v[2:3] offset:2048
	s_or_b64 exec, exec, s[6:7]
	v_cndmask_b32_e64 v0, 0, 1, s[12:13]
	v_cmp_ne_u32_e64 s[6:7], 1, v0
	s_andn2_b64 vcc, exec, s[12:13]
	s_waitcnt lgkmcnt(0)
	s_barrier
	s_cbranch_vccnz .LBB0_340
	s_cmp_lt_u32 s62, 8
	s_cbranch_scc1 .LBB0_341
	s_add_i32 s9, 16, 0x800
	s_and_b32 s8, s62, 0x7ffffff8
	v_add3_u32 v151, v141, v138, s9
	v_mov_b32_e32 v0, 1.0
	v_mov_b32_e32 v3, 0
	s_mov_b32 s9, 0

.LBB0_344:
	ds_read_b128 v[178:181], v148 offset:32768
	ds_read_b128 v[182:185], v150 offset:32768
	v_add_u32_e32 v242, 0x8000, v148
	ds_read_b128 v[186:189], v242 offset:32768
	v_add_u32_e32 v242, 0x8000, v150
	ds_read_b128 v[190:193], v242 offset:32768
	ds_read_b128 v[194:197], v145 offset:32768
	ds_read_b128 v[198:201], v149 offset:32768
	v_add_u32_e32 v242, 0x8000, v149
	ds_read_b128 v[202:205], v242 offset:32768
	v_add_u32_e32 v242, 0x8000, v145
	ds_read_b128 v[206:209], v242 offset:32768
	ds_read_b128 v[210:213], v144 offset:32768
	ds_read_b128 v[214:217], v147 offset:32768
	v_add_u32_e32 v242, 0x8000, v147
	ds_read_b128 v[218:221], v242 offset:32768
	v_add_u32_e32 v242, 0x8000, v144
	ds_read_b128 v[222:225], v242 offset:32768
	ds_read_b128 v[226:229], v143 offset:32768
	ds_read_b128 v[230:233], v146 offset:32768
	v_add_u32_e32 v242, 0x8000, v146
	ds_read_b128 v[234:237], v242 offset:32768
	v_add_u32_e32 v242, 0x8000, v143
	ds_read_b128 v[238:241], v242 offset:32768
	v_cndmask_b32_e64 v1, v13, 1.0, s[0:1]
	v_cndmask_b32_e64 v2, v10, 0, s[0:1]
	v_cndmask_b32_e64 v10, v42, v15, s[0:1]
	v_cndmask_b32_e64 v13, v17, v14, s[0:1]
	v_cndmask_b32_e64 v14, v46, v43, s[0:1]
	v_cndmask_b32_e64 v15, v44, v41, s[0:1]
	v_cndmask_b32_e64 v17, v93, v47, s[0:1]
	v_cndmask_b32_e64 v41, v91, v45, s[0:1]
	v_fmac_f32_e32 v18, v32, v2
	v_mul_f32_e32 v32, v1, v32
	v_fmac_f32_e32 v31, v33, v2
	v_mul_f32_e32 v33, v1, v33
	v_fmac_f32_e32 v30, v34, v2
	v_mul_f32_e32 v34, v1, v34
	v_fmac_f32_e32 v29, v35, v2
	v_mul_f32_e32 v1, v1, v35
	v_fmac_f32_e32 v27, v37, v13
	v_mul_f32_e32 v35, v37, v10
	v_fmac_f32_e32 v24, v40, v15
	v_mul_f32_e32 v37, v40, v14
	v_fmac_f32_e32 v9, v4, v41
	v_mul_f32_e32 v40, v4, v17
	v_mul_f32_e32 v4, v32, v0
	v_fmac_f32_e32 v18, v32, v3
	v_cvt_pk_bf16_f32 v4, v18, v4
	v_fmac_f32_e32 v19, v20, v13
	v_mul_f32_e32 v2, v20, v10
	v_fmac_f32_e32 v28, v36, v13
	v_mul_f32_e32 v20, v36, v10
	v_fmac_f32_e32 v26, v38, v13
	v_mul_f32_e32 v10, v38, v10
	v_fmac_f32_e32 v23, v12, v15
	v_mul_f32_e32 v38, v12, v14
	v_lshl_add_u64 v[12:13], v[94:95], 0, s[38:39]
	global_load_dword v172, v[130:131], off offset:256
	global_load_dword v173, v[126:127], off offset:256
	global_load_dword v174, v[128:129], off offset:256
	global_store_dword v[96:97], v4, off offset:128 nt
	v_mul_f32_e32 v4, v33, v0
	v_fmac_f32_e32 v21, v22, v15
	v_mul_f32_e32 v22, v22, v14
	v_fmac_f32_e32 v25, v39, v15
	v_mul_f32_e32 v36, v39, v14
	v_fmac_f32_e32 v31, v33, v3
	v_cvt_pk_bf16_f32 v4, v31, v4
	v_lshl_add_u64 v[14:15], v[12:13], 0, v[88:89]
	global_store_dword v[14:15], v4, off nt
	v_mul_f32_e32 v4, v34, v0
	v_lshl_add_u64 v[14:15], v[12:13], 0, v[98:99]
	v_fmac_f32_e32 v29, v1, v3
	v_mul_f32_e32 v1, v1, v0
	v_fmac_f32_e32 v30, v34, v3
	v_cvt_pk_bf16_f32 v4, v30, v4
	global_store_dword v[14:15], v4, off nt
	v_cvt_pk_bf16_f32 v1, v29, v1
	v_lshl_add_u64 v[14:15], v[12:13], 0, v[100:101]
	global_store_dword v[14:15], v1, off nt
	v_mul_f32_e32 v1, v2, v0
	v_fmac_f32_e32 v19, v2, v3
	v_cvt_pk_bf16_f32 v1, v19, v1
	v_lshl_add_u64 v[14:15], v[12:13], 0, v[102:103]
	global_store_dword v[14:15], v1, off nt
	v_mul_f32_e32 v1, v20, v0
	v_fmac_f32_e32 v28, v20, v3
	v_cvt_pk_bf16_f32 v1, v28, v1
	v_lshl_add_u64 v[14:15], v[12:13], 0, v[104:105]
	global_store_dword v[14:15], v1, off nt
	v_mul_f32_e32 v1, v35, v0
	v_fmac_f32_e32 v27, v35, v3
	v_cvt_pk_bf16_f32 v1, v27, v1
	v_lshl_add_u64 v[14:15], v[12:13], 0, v[106:107]
	global_store_dword v[14:15], v1, off nt
	v_mul_f32_e32 v1, v10, v0
	v_fmac_f32_e32 v26, v10, v3
	v_cvt_pk_bf16_f32 v1, v26, v1
	v_lshl_add_u64 v[14:15], v[12:13], 0, v[108:109]
	global_store_dword v[14:15], v1, off nt
	v_mul_f32_e32 v1, v22, v0
	v_fmac_f32_e32 v21, v22, v3
	v_cvt_pk_bf16_f32 v1, v21, v1
	v_lshl_add_u64 v[14:15], v[12:13], 0, v[110:111]
	global_store_dword v[14:15], v1, off nt
	v_mul_f32_e32 v1, v36, v0
	v_fmac_f32_e32 v25, v36, v3
	v_cvt_pk_bf16_f32 v1, v25, v1
	v_lshl_add_u64 v[14:15], v[12:13], 0, v[112:113]
	global_store_dword v[14:15], v1, off nt
	v_mul_f32_e32 v1, v37, v0
	v_fmac_f32_e32 v24, v37, v3
	v_cvt_pk_bf16_f32 v1, v24, v1
	v_lshl_add_u64 v[14:15], v[12:13], 0, v[114:115]
	global_store_dword v[14:15], v1, off nt
	v_mul_f32_e32 v1, v38, v0
	v_fmac_f32_e32 v6, v16, v41
	v_mul_f32_e32 v16, v16, v17
	v_fmac_f32_e32 v23, v38, v3
	v_cvt_pk_bf16_f32 v1, v23, v1
	v_lshl_add_u64 v[14:15], v[12:13], 0, v[116:117]
	global_store_dword v[14:15], v1, off nt
	v_fmac_f32_e32 v6, v16, v3
	v_mul_f32_e32 v1, v16, v0
	v_fmac_f32_e32 v5, v7, v41
	v_mul_f32_e32 v39, v7, v17
	v_cvt_pk_bf16_f32 v1, v6, v1
	v_lshl_add_u64 v[6:7], v[12:13], 0, v[118:119]
	global_store_dword v[6:7], v1, off nt
	v_fmac_f32_e32 v5, v39, v3
	v_mul_f32_e32 v1, v39, v0
	v_cvt_pk_bf16_f32 v1, v5, v1
	v_lshl_add_u64 v[4:5], v[12:13], 0, v[120:121]
	v_fmac_f32_e32 v11, v8, v41
	v_mul_f32_e32 v8, v8, v17
	global_store_dword v[4:5], v1, off nt
	v_mul_f32_e32 v1, v40, v0
	v_fmac_f32_e32 v9, v40, v3
	v_cvt_pk_bf16_f32 v1, v9, v1
	v_lshl_add_u64 v[4:5], v[12:13], 0, v[122:123]
	v_mul_f32_e32 v0, v8, v0
	global_store_dword v[4:5], v1, off nt
	v_fmac_f32_e32 v11, v8, v3
	v_cvt_pk_bf16_f32 v2, v11, v0
	v_lshl_add_u64 v[0:1], v[12:13], 0, v[124:125]
	global_store_dword v[0:1], v2, off nt
	s_and_saveexec_b64 s[8:9], s[4:5]
	s_cbranch_execz .LBB0_346
	v_add_u32_e32 v12, 0x800, v142
	ds_read2_b64 v[0:3], v12 offset1:32
	ds_read2_b64 v[4:7], v12 offset0:64 offset1:96
	ds_read2_b64 v[8:11], v12 offset0:128 offset1:160
	ds_read2_b64 v[12:15], v12 offset0:192 offset1:224
	s_waitcnt lgkmcnt(3)
	v_fma_f32 v16, 0, v0, v1
	v_pk_mul_f32 v[0:1], v[0:1], v[2:3]
	v_fma_f32 v2, v2, v16, v3
	s_waitcnt lgkmcnt(2)
	v_fma_f32 v2, v4, v2, v5
	v_fma_f32 v2, v6, v2, v7
	s_waitcnt lgkmcnt(1)
	v_fma_f32 v3, v8, v2, v9
	v_mov_b32_e32 v2, v0
	v_mov_b32_e32 v16, v4
	v_mov_b32_e32 v17, v10
	v_pk_mul_f32 v[0:1], v[0:1], v[4:5]
	v_pk_fma_f32 v[2:3], v[2:3], v[16:17], v[10:11]
	v_pk_mul_f32 v[0:1], v[0:1], v[6:7]
	s_waitcnt lgkmcnt(0)
	v_mov_b32_e32 v9, v12
	v_mov_b32_e32 v1, v3
	v_pk_mul_f32 v[2:3], v[0:1], v[8:9]
	v_pk_fma_f32 v[0:1], v[0:1], v[8:9], v[12:13]
	v_pk_mul_f32 v[2:3], v[2:3], v[10:11]
	v_mov_b32_e32 v4, v12
	v_mov_b32_e32 v0, v2
	v_mov_b32_e32 v5, v14
	v_pk_mul_f32 v[2:3], v[2:3], v[12:13]
	v_pk_fma_f32 v[0:1], v[0:1], v[4:5], v[14:15]
	v_pk_mul_f32 v[2:3], v[2:3], v[14:15]
	v_add_u32_e32 v0, 32, v92
	v_mov_b32_e32 v3, v1
	v_ashrrev_i32_e32 v1, 31, v0
	v_lshl_add_u64 v[0:1], v[0:1], 3, s[24:25]
	global_store_dwordx2 v[0:1], v[2:3], off
.LBB0_346:
	s_or_b64 exec, exec, s[8:9]
	s_setprio 1
	s_waitcnt lgkmcnt(0)
	v_mfma_f32_32x32x16_bf16 v[16:31], v[48:51], v[178:181], 0
	v_mfma_f32_32x32x16_bf16 v[32:47], v[48:51], v[186:189], 0
	v_mfma_f32_32x32x16_bf16 v[16:31], v[52:55], v[182:185], v[16:31]
	v_mfma_f32_32x32x16_bf16 v[32:47], v[52:55], v[190:193], v[32:47]
	v_mfma_f32_32x32x16_bf16 v[16:31], v[56:59], v[194:197], v[16:31]
	v_mfma_f32_32x32x16_bf16 v[32:47], v[56:59], v[206:209], v[32:47]
	v_mfma_f32_32x32x16_bf16 v[16:31], v[60:63], v[198:201], v[16:31]
	v_mfma_f32_32x32x16_bf16 v[32:47], v[60:63], v[202:205], v[32:47]
	v_mfma_f32_32x32x16_bf16 v[16:31], v[64:67], v[210:213], v[16:31]
	v_mfma_f32_32x32x16_bf16 v[32:47], v[64:67], v[222:225], v[32:47]
	v_mfma_f32_32x32x16_bf16 v[16:31], v[68:71], v[214:217], v[16:31]
	v_mfma_f32_32x32x16_bf16 v[32:47], v[68:71], v[218:221], v[32:47]
	v_mfma_f32_32x32x16_bf16 v[16:31], v[72:75], v[226:229], v[16:31]
	v_mfma_f32_32x32x16_bf16 v[32:47], v[72:75], v[238:241], v[32:47]
	v_mfma_f32_32x32x16_bf16 v[16:31], v[76:79], v[230:233], v[16:31]
	v_mfma_f32_32x32x16_bf16 v[32:47], v[76:79], v[234:237], v[32:47]
	v_mfma_f32_32x32x16_bf16 v[0:15], v[64:67], v[80:83], 0
	v_mfma_f32_32x32x16_bf16 v[0:15], v[68:71], v[84:87], v[0:15]
	s_setprio 0
	s_waitcnt vmcnt(16)
	ds_read_b32 v251, v167 offset:256
	v_mul_f32_e32 v151, 0xbfb8aa3b, v173
	v_mul_f32_e32 v93, 0xbfb8aa3b, v174
	s_nop 0
	v_fmamk_f32 v18, v18, 0xbfb8aa3b, v151
	v_fmamk_f32 v19, v19, 0xbfb8aa3b, v151
	v_fmamk_f32 v16, v16, 0xbfb8aa3b, v151
	v_fmamk_f32 v32, v32, 0xbfb8aa3b, v93
	v_fmamk_f32 v17, v17, 0xbfb8aa3b, v151
	v_exp_f32_e32 v18, v18
	v_fmamk_f32 v33, v33, 0xbfb8aa3b, v93
	v_exp_f32_e32 v161, v19
	v_exp_f32_e32 v91, v16
	v_exp_f32_e32 v32, v32
	v_exp_f32_e32 v152, v17
	v_exp_f32_e32 v33, v33
	v_add_f32_e32 v162, 1.0, v18
	v_add_f32_e32 v32, 1.0, v32
	v_add_f32_e32 v91, 1.0, v91
	v_add_f32_e32 v33, 1.0, v33
	v_rcp_f32_e32 v164, v32
	v_rcp_f32_e32 v163, v91
	v_rcp_f32_e32 v166, v33
	v_add_f32_e32 v152, 1.0, v152
	v_rcp_f32_e32 v165, v152
	v_fmamk_f32 v34, v34, 0xbfb8aa3b, v93
	v_exp_f32_e32 v34, v34
	v_fmamk_f32 v36, v36, 0xbfb8aa3b, v93
	v_add_f32_e32 v34, 1.0, v34
	v_exp_f32_e32 v36, v36
	s_nop 1
	s_nop 1
	s_waitcnt lgkmcnt(0)
	v_mul_f32_e32 v33, 0x3fb8aa3b, v251
	v_mul_f32_e32 v16, v163, v33
	v_exp_f32_e32 v32, v16
	v_rcp_f32_e32 v16, v162
	v_mul_f32_e32 v17, v165, v33
	v_fma_f32 v18, -v32, v32, 1.0
	v_sqrt_f32_e32 v18, v18
	v_mul_f32_e32 v16, v16, v33
	v_exp_f32_e32 v91, v17
	v_mul_f32_e32 v18, v164, v18
	v_mul_f32_e32 v18, v0, v18
	v_exp_f32_e32 v0, v16
	v_add_f32_e32 v16, 1.0, v161
	v_rcp_f32_e32 v16, v16
	v_fma_f32 v19, -v91, v91, 1.0
	v_sqrt_f32_e32 v19, v19
	v_rcp_f32_e32 v17, v34
	v_mul_f32_e32 v16, v16, v33
	v_exp_f32_e32 v152, v16
	v_fmamk_f32 v16, v20, 0xbfb8aa3b, v151
	v_mul_f32_e32 v34, v166, v19
	v_fmamk_f32 v19, v35, 0xbfb8aa3b, v93
	v_exp_f32_e32 v16, v16
	v_exp_f32_e32 v19, v19
	v_fma_f32 v20, -v152, v152, 1.0
	v_add_f32_e32 v16, 1.0, v16
	v_rcp_f32_e32 v16, v16
	v_add_f32_e32 v19, 1.0, v19
	v_rcp_f32_e32 v19, v19
	v_sqrt_f32_e32 v20, v20
	v_mul_f32_e32 v16, v16, v33
	v_fma_f32 v35, -v0, v0, 1.0
	v_mul_f32_e32 v153, v19, v20
	v_exp_f32_e32 v20, v16
	v_fmamk_f32 v16, v21, 0xbfb8aa3b, v151
	v_exp_f32_e32 v16, v16
	v_sqrt_f32_e32 v35, v35
	v_fma_f32 v19, -v20, v20, 1.0
	v_fmamk_f32 v21, v37, 0xbfb8aa3b, v93
	v_add_f32_e32 v16, 1.0, v16
	v_rcp_f32_e32 v16, v16
	v_mul_f32_e32 v35, v17, v35
	v_add_f32_e32 v17, 1.0, v36
	v_rcp_f32_e32 v17, v17
	v_mul_f32_e32 v16, v16, v33
	v_exp_f32_e32 v36, v16
	v_fmamk_f32 v16, v22, 0xbfb8aa3b, v151
	v_exp_f32_e32 v16, v16
	v_sqrt_f32_e32 v19, v19
	v_exp_f32_e32 v21, v21
	v_add_f32_e32 v16, 1.0, v16
	v_rcp_f32_e32 v16, v16
	v_mul_f32_e32 v17, v17, v19
	v_mul_f32_e32 v19, v4, v17
	v_add_f32_e32 v4, 1.0, v21
	v_fmamk_f32 v21, v38, 0xbfb8aa3b, v93
	v_mul_f32_e32 v16, v16, v33
	v_fma_f32 v17, -v36, v36, 1.0
	v_exp_f32_e32 v21, v21
	v_rcp_f32_e32 v4, v4
	v_sqrt_f32_e32 v17, v17
	v_exp_f32_e32 v37, v16
	v_add_f32_e32 v16, 1.0, v21
	v_fmamk_f32 v21, v23, 0xbfb8aa3b, v151
	v_mul_f32_e32 v4, v4, v17
	v_fma_f32 v17, -v37, v37, 1.0
	v_rcp_f32_e32 v16, v16
	v_sqrt_f32_e32 v17, v17
	v_exp_f32_e32 v21, v21
	v_fmamk_f32 v22, v39, 0xbfb8aa3b, v93
	v_mul_f32_e32 v23, v16, v17
	v_add_f32_e32 v16, 1.0, v21
	v_rcp_f32_e32 v16, v16
	v_fmamk_f32 v21, v24, 0xbfb8aa3b, v151
	v_exp_f32_e32 v21, v21
	v_mul_f32_e32 v16, v16, v33
	v_exp_f32_e32 v24, v16
	v_add_f32_e32 v16, 1.0, v21
	v_rcp_f32_e32 v16, v16
	v_exp_f32_e32 v22, v22
	v_fmamk_f32 v21, v40, 0xbfb8aa3b, v93
	v_mul_f32_e32 v16, v16, v33
	v_add_f32_e32 v17, 1.0, v22
	v_fma_f32 v22, -v24, v24, 1.0
	v_sqrt_f32_e32 v38, v22
	v_exp_f32_e32 v22, v16
	v_fmamk_f32 v16, v25, 0xbfb8aa3b, v151
	v_exp_f32_e32 v16, v16
	v_exp_f32_e32 v21, v21
	v_fmamk_f32 v39, v41, 0xbfb8aa3b, v93
	v_fma_f32 v25, -v22, v22, 1.0
	v_add_f32_e32 v16, 1.0, v16
	v_rcp_f32_e32 v16, v16
	v_add_f32_e32 v21, 1.0, v21
	v_rcp_f32_e32 v17, v17
	v_rcp_f32_e32 v21, v21
	v_sqrt_f32_e32 v25, v25
	v_exp_f32_e32 v39, v39
	v_mul_f32_e32 v16, v16, v33
	v_mul_f32_e32 v38, v17, v38
	v_mul_f32_e32 v17, v21, v25
	v_add_f32_e32 v21, 1.0, v39
	v_exp_f32_e32 v39, v16
	v_fmamk_f32 v16, v26, 0xbfb8aa3b, v151
	v_exp_f32_e32 v16, v16
	v_rcp_f32_e32 v25, v21
	v_fma_f32 v21, -v39, v39, 1.0
	v_sqrt_f32_e32 v26, v21
	v_add_f32_e32 v16, 1.0, v16
	v_fmamk_f32 v21, v42, 0xbfb8aa3b, v93
	v_rcp_f32_e32 v16, v16
	v_exp_f32_e32 v40, v21
	v_mul_f32_e32 v21, v8, v17
	v_mul_f32_e32 v16, v16, v33
	v_add_f32_e32 v17, 1.0, v40
	v_exp_f32_e32 v40, v16
	v_fmamk_f32 v16, v27, 0xbfb8aa3b, v151
	v_exp_f32_e32 v16, v16
	v_mul_f32_e32 v8, v25, v26
	v_fma_f32 v25, -v40, v40, 1.0
	v_fmamk_f32 v26, v43, 0xbfb8aa3b, v93
	v_add_f32_e32 v16, 1.0, v16
	v_rcp_f32_e32 v16, v16
	v_rcp_f32_e32 v17, v17
	v_sqrt_f32_e32 v25, v25
	v_mul_f32_e32 v16, v16, v33
	v_exp_f32_e32 v26, v26
	v_exp_f32_e32 v41, v16
	v_mul_f32_e32 v154, v17, v25
	v_fmamk_f32 v25, v28, 0xbfb8aa3b, v151
	v_add_f32_e32 v16, 1.0, v26
	v_fmamk_f32 v26, v44, 0xbfb8aa3b, v93
	v_fma_f32 v17, -v41, v41, 1.0
	v_exp_f32_e32 v25, v25
	v_rcp_f32_e32 v16, v16
	v_sqrt_f32_e32 v17, v17
	v_exp_f32_e32 v26, v26
	v_add_f32_e32 v25, 1.0, v25
	v_rcp_f32_e32 v25, v25
	v_mul_f32_e32 v155, v16, v17
	v_add_f32_e32 v16, 1.0, v26
	v_fmamk_f32 v26, v45, 0xbfb8aa3b, v93
	v_exp_f32_e32 v26, v26
	v_rcp_f32_e32 v17, v16
	v_mul_f32_e32 v16, v25, v33
	v_fmamk_f32 v25, v29, 0xbfb8aa3b, v151
	v_exp_f32_e32 v25, v25
	v_add_f32_e32 v26, 1.0, v26
	v_rcp_f32_e32 v42, v26
	v_fmamk_f32 v26, v30, 0xbfb8aa3b, v151
	v_exp_f32_e32 v26, v26
	v_add_f32_e32 v25, 1.0, v25
	v_rcp_f32_e32 v25, v25
	v_fmamk_f32 v27, v46, 0xbfb8aa3b, v93
	v_exp_f32_e32 v27, v27
	v_add_f32_e32 v26, 1.0, v26
	v_rcp_f32_e32 v26, v26
	v_mul_f32_e32 v25, v25, v33
	v_exp_f32_e32 v43, v25
	v_add_f32_e32 v25, 1.0, v27
	v_rcp_f32_e32 v44, v25
	v_mul_f32_e32 v25, v26, v33
	v_fmamk_f32 v26, v31, 0xbfb8aa3b, v151
	v_exp_f32_e32 v26, v26
	v_fmamk_f32 v27, v47, 0xbfb8aa3b, v93
	v_exp_f32_e32 v27, v27
	v_add_f32_e32 v26, 1.0, v26
	v_rcp_f32_e32 v26, v26
	v_exp_f32_e32 v16, v16
	v_fmac_f32_e32 v18, 0, v32
	v_exp_f32_e32 v45, v25
	v_add_f32_e32 v25, 1.0, v27
	v_mul_f32_e32 v31, v91, v18
	v_rcp_f32_e32 v46, v25
	v_mul_f32_e32 v25, v26, v33
	v_fmac_f32_e32 v31, v1, v34
	v_mul_f32_e32 v33, v32, v91
	v_fmac_f32_e32 v19, 0, v20
	v_mul_f32_e32 v30, v0, v31
	v_mul_f32_e32 v34, v0, v33
	v_mul_f32_e32 v28, v36, v19
	v_fma_f32 v0, -v16, v16, 1.0
	v_fmac_f32_e32 v28, v5, v4
	v_sqrt_f32_e32 v1, v0
	v_mul_f32_e32 v27, v37, v28
	v_fmac_f32_e32 v30, v2, v35
	v_fmac_f32_e32 v27, v6, v23
	v_fma_f32 v2, -v43, v43, 1.0
	v_mul_f32_e32 v26, v24, v27
	v_mov_b32_e32 v0, v89
	v_sqrt_f32_e32 v2, v2
	v_fmac_f32_e32 v26, v7, v38
	v_pk_mul_f32 v[6:7], v[16:17], v[0:1]
	v_mul_f32_e32 v29, v152, v30
	v_fmac_f32_e32 v6, v12, v7
	v_fmac_f32_e32 v29, v3, v153
	v_mov_b32_e32 v3, v6
	v_pk_mul_f32 v[4:5], v[42:43], v[2:3]
	v_fma_f32 v0, -v45, v45, 1.0
	v_exp_f32_e32 v47, v25
	v_fmac_f32_e32 v5, v13, v4
	v_sqrt_f32_e32 v4, v0
	v_fmac_f32_e32 v21, 0, v22
	v_mul_f32_e32 v25, v39, v21
	v_mul_f32_e32 v36, v20, v36
	v_fmac_f32_e32 v25, v9, v8
	v_pk_mul_f32 v[8:9], v[44:45], v[4:5]
	v_fma_f32 v0, -v47, v47, 1.0
	v_mul_f32_e32 v37, v37, v36
	v_fmac_f32_e32 v9, v14, v8
	v_sqrt_f32_e32 v8, v0
	ds_bpermute_b32 v0, v140, v29
	v_mul_f32_e32 v38, v24, v37
	v_mul_f32_e32 v24, v40, v25
	v_mul_f32_e32 v35, v152, v34
	v_fmac_f32_e32 v24, v10, v154
	v_mul_f32_e32 v23, v41, v24
	ds_bpermute_b32 v13, v140, v35
	v_fmac_f32_e32 v23, v11, v155
	v_pk_mul_f32 v[10:11], v[46:47], v[8:9]
	s_waitcnt lgkmcnt(1)
	v_cndmask_b32_e64 v14, v29, v0, s[0:1]
	v_fmac_f32_e32 v11, v15, v10
	v_cndmask_b32_e64 v10, v0, v29, s[0:1]
	ds_bpermute_b32 v0, v140, v38
	ds_bpermute_b32 v3, v140, v26
	v_mul_f32_e32 v39, v22, v39
	v_mul_f32_e32 v40, v40, v39
	s_waitcnt lgkmcnt(2)
	v_cndmask_b32_e64 v1, v13, v35, s[0:1]
	v_mul_f32_e32 v12, v41, v40
	v_mul_f32_e32 v7, v16, v43
	v_cndmask_b32_e64 v2, v35, v13, s[0:1]
	v_fmac_f32_e32 v10, 0, v1
	v_mul_f32_e32 v4, v45, v7
	v_mul_f32_e32 v15, v35, v13
	v_fmac_f32_e32 v14, v2, v10
	s_waitcnt lgkmcnt(1)
	v_cndmask_b32_e64 v1, v0, v38, s[0:1]
	s_waitcnt lgkmcnt(0)
	v_cndmask_b32_e64 v17, v3, v26, s[0:1]
	v_cndmask_b32_e64 v41, v26, v3, s[0:1]
	ds_bpermute_b32 v2, v140, v12
	ds_bpermute_b32 v3, v140, v23
	v_mul_f32_e32 v8, v47, v4
	v_cndmask_b32_e64 v0, v38, v0, s[0:1]
	v_mul_f32_e32 v42, v15, v1
	v_fmac_f32_e32 v17, v1, v14
	v_mul_f32_e32 v43, v0, v42
	v_fmac_f32_e32 v41, v0, v17
	ds_bpermute_b32 v1, v140, v8
	ds_bpermute_b32 v0, v140, v11
	s_waitcnt lgkmcnt(3)
	v_cndmask_b32_e64 v47, v2, v12, s[0:1]
	s_waitcnt lgkmcnt(2)
	v_cndmask_b32_e64 v44, v3, v23, s[0:1]
	v_cndmask_b32_e64 v2, v12, v2, s[0:1]
	v_cndmask_b32_e64 v45, v23, v3, s[0:1]
	v_mul_f32_e32 v46, v47, v43
	v_fmac_f32_e32 v44, v47, v41
	v_mul_f32_e32 v47, v2, v46
	v_fmac_f32_e32 v45, v2, v44
	s_waitcnt lgkmcnt(1)
	v_cndmask_b32_e64 v2, v1, v8, s[0:1]
	s_waitcnt lgkmcnt(0)
	v_cndmask_b32_e64 v91, v0, v11, s[0:1]
	v_mul_f32_e32 v93, v2, v47
	v_fmac_f32_e32 v91, v2, v45
	s_and_saveexec_b64 s[8:9], s[0:1]
	v_mul_f32_e32 v3, v91, v1
	v_mul_f32_e32 v2, v93, v1
	v_add_f32_e32 v3, v3, v0
	ds_write_b64 v139, v[2:3] offset:4096
	s_or_b64 exec, exec, s[8:9]
	s_and_b64 vcc, exec, s[6:7]
	s_waitcnt lgkmcnt(0)
	s_barrier
	s_cbranch_vccnz .LBB0_353
	s_cmp_lt_u32 s62, 8
	s_cbranch_scc1 .LBB0_354
	s_add_i32 s9, 16, 0x1000
	s_and_b32 s8, s62, 0x7ffffff8
	v_add3_u32 v151, v141, v138, s9
	v_mov_b32_e32 v0, 1.0
	v_mov_b32_e32 v3, 0
	s_mov_b32 s9, 0

.LBB0_357:
	ds_read_b128 v[178:181], v148 offset:40960
	ds_read_b128 v[182:185], v150 offset:40960
	v_add_u32_e32 v242, 0xa000, v148
	ds_read_b128 v[186:189], v242 offset:32768
	v_add_u32_e32 v242, 0xa000, v150
	ds_read_b128 v[190:193], v242 offset:32768
	ds_read_b128 v[194:197], v145 offset:40960
	ds_read_b128 v[198:201], v149 offset:40960
	v_add_u32_e32 v242, 0xa000, v149
	ds_read_b128 v[202:205], v242 offset:32768
	v_add_u32_e32 v242, 0xa000, v145
	ds_read_b128 v[206:209], v242 offset:32768
	ds_read_b128 v[210:213], v144 offset:40960
	ds_read_b128 v[214:217], v147 offset:40960
	v_add_u32_e32 v242, 0xa000, v147
	ds_read_b128 v[218:221], v242 offset:32768
	v_add_u32_e32 v242, 0xa000, v144
	ds_read_b128 v[222:225], v242 offset:32768
	ds_read_b128 v[226:229], v143 offset:40960
	ds_read_b128 v[230:233], v146 offset:40960
	v_add_u32_e32 v242, 0xa000, v146
	ds_read_b128 v[234:237], v242 offset:32768
	v_add_u32_e32 v242, 0xa000, v143
	ds_read_b128 v[238:241], v242 offset:32768
	v_cndmask_b32_e64 v1, v13, 1.0, s[0:1]
	v_cndmask_b32_e64 v2, v10, 0, s[0:1]
	v_cndmask_b32_e64 v10, v42, v15, s[0:1]
	v_cndmask_b32_e64 v13, v17, v14, s[0:1]
	v_cndmask_b32_e64 v14, v46, v43, s[0:1]
	v_cndmask_b32_e64 v15, v44, v41, s[0:1]
	v_cndmask_b32_e64 v17, v93, v47, s[0:1]
	v_cndmask_b32_e64 v41, v91, v45, s[0:1]
	v_fmac_f32_e32 v18, v32, v2
	v_mul_f32_e32 v32, v1, v32
	v_fmac_f32_e32 v31, v33, v2
	v_mul_f32_e32 v33, v1, v33
	v_fmac_f32_e32 v30, v34, v2
	v_mul_f32_e32 v34, v1, v34
	v_fmac_f32_e32 v29, v35, v2
	v_mul_f32_e32 v1, v1, v35
	v_fmac_f32_e32 v27, v37, v13
	v_mul_f32_e32 v35, v37, v10
	v_fmac_f32_e32 v24, v40, v15
	v_mul_f32_e32 v37, v40, v14
	v_fmac_f32_e32 v9, v4, v41
	v_mul_f32_e32 v40, v4, v17
	v_mul_f32_e32 v4, v32, v0
	v_fmac_f32_e32 v18, v32, v3
	v_cvt_pk_bf16_f32 v4, v18, v4
	v_fmac_f32_e32 v19, v20, v13
	v_mul_f32_e32 v2, v20, v10
	v_fmac_f32_e32 v28, v36, v13
	v_mul_f32_e32 v20, v36, v10
	v_fmac_f32_e32 v26, v38, v13
	v_mul_f32_e32 v10, v38, v10
	v_fmac_f32_e32 v23, v12, v15
	v_mul_f32_e32 v38, v12, v14
	v_lshl_add_u64 v[12:13], v[94:95], 0, s[48:49]
	global_load_dword v172, v[130:131], off offset:384
	global_load_dword v173, v[126:127], off offset:384
	global_load_dword v174, v[128:129], off offset:384
	global_store_dword v[96:97], v4, off offset:256 nt
	v_mul_f32_e32 v4, v33, v0
	v_fmac_f32_e32 v21, v22, v15
	v_mul_f32_e32 v22, v22, v14
	v_fmac_f32_e32 v25, v39, v15
	v_mul_f32_e32 v36, v39, v14
	v_fmac_f32_e32 v31, v33, v3
	v_cvt_pk_bf16_f32 v4, v31, v4
	v_lshl_add_u64 v[14:15], v[12:13], 0, v[88:89]
	global_store_dword v[14:15], v4, off nt
	v_mul_f32_e32 v4, v34, v0
	v_lshl_add_u64 v[14:15], v[12:13], 0, v[98:99]
	v_fmac_f32_e32 v29, v1, v3
	v_mul_f32_e32 v1, v1, v0
	v_fmac_f32_e32 v30, v34, v3
	v_cvt_pk_bf16_f32 v4, v30, v4
	global_store_dword v[14:15], v4, off nt
	v_cvt_pk_bf16_f32 v1, v29, v1
	v_lshl_add_u64 v[14:15], v[12:13], 0, v[100:101]
	global_store_dword v[14:15], v1, off nt
	v_mul_f32_e32 v1, v2, v0
	v_fmac_f32_e32 v19, v2, v3
	v_cvt_pk_bf16_f32 v1, v19, v1
	v_lshl_add_u64 v[14:15], v[12:13], 0, v[102:103]
	global_store_dword v[14:15], v1, off nt
	v_mul_f32_e32 v1, v20, v0
	v_fmac_f32_e32 v28, v20, v3
	v_cvt_pk_bf16_f32 v1, v28, v1
	v_lshl_add_u64 v[14:15], v[12:13], 0, v[104:105]
	global_store_dword v[14:15], v1, off nt
	v_mul_f32_e32 v1, v35, v0
	v_fmac_f32_e32 v27, v35, v3
	v_cvt_pk_bf16_f32 v1, v27, v1
	v_lshl_add_u64 v[14:15], v[12:13], 0, v[106:107]
	global_store_dword v[14:15], v1, off nt
	v_mul_f32_e32 v1, v10, v0
	v_fmac_f32_e32 v26, v10, v3
	v_cvt_pk_bf16_f32 v1, v26, v1
	v_lshl_add_u64 v[14:15], v[12:13], 0, v[108:109]
	global_store_dword v[14:15], v1, off nt
	v_mul_f32_e32 v1, v22, v0
	v_fmac_f32_e32 v21, v22, v3
	v_cvt_pk_bf16_f32 v1, v21, v1
	v_lshl_add_u64 v[14:15], v[12:13], 0, v[110:111]
	global_store_dword v[14:15], v1, off nt
	v_mul_f32_e32 v1, v36, v0
	v_fmac_f32_e32 v25, v36, v3
	v_cvt_pk_bf16_f32 v1, v25, v1
	v_lshl_add_u64 v[14:15], v[12:13], 0, v[112:113]
	global_store_dword v[14:15], v1, off nt
	v_mul_f32_e32 v1, v37, v0
	v_fmac_f32_e32 v24, v37, v3
	v_cvt_pk_bf16_f32 v1, v24, v1
	v_lshl_add_u64 v[14:15], v[12:13], 0, v[114:115]
	global_store_dword v[14:15], v1, off nt
	v_mul_f32_e32 v1, v38, v0
	v_fmac_f32_e32 v6, v16, v41
	v_mul_f32_e32 v16, v16, v17
	v_fmac_f32_e32 v23, v38, v3
	v_cvt_pk_bf16_f32 v1, v23, v1
	v_lshl_add_u64 v[14:15], v[12:13], 0, v[116:117]
	global_store_dword v[14:15], v1, off nt
	v_fmac_f32_e32 v6, v16, v3
	v_mul_f32_e32 v1, v16, v0
	v_fmac_f32_e32 v5, v7, v41
	v_mul_f32_e32 v39, v7, v17
	v_cvt_pk_bf16_f32 v1, v6, v1
	v_lshl_add_u64 v[6:7], v[12:13], 0, v[118:119]
	global_store_dword v[6:7], v1, off nt
	v_fmac_f32_e32 v5, v39, v3
	v_mul_f32_e32 v1, v39, v0
	v_cvt_pk_bf16_f32 v1, v5, v1
	v_lshl_add_u64 v[4:5], v[12:13], 0, v[120:121]
	v_fmac_f32_e32 v11, v8, v41
	v_mul_f32_e32 v8, v8, v17
	global_store_dword v[4:5], v1, off nt
	v_mul_f32_e32 v1, v40, v0
	v_fmac_f32_e32 v9, v40, v3
	v_cvt_pk_bf16_f32 v1, v9, v1
	v_lshl_add_u64 v[4:5], v[12:13], 0, v[122:123]
	v_mul_f32_e32 v0, v8, v0
	global_store_dword v[4:5], v1, off nt
	v_fmac_f32_e32 v11, v8, v3
	v_cvt_pk_bf16_f32 v2, v11, v0
	v_lshl_add_u64 v[0:1], v[12:13], 0, v[124:125]
	global_store_dword v[0:1], v2, off nt
	s_and_saveexec_b64 s[8:9], s[4:5]
	s_cbranch_execz .LBB0_359
	v_add_u32_e32 v12, 0x1000, v142
	ds_read2_b64 v[0:3], v12 offset1:32
	ds_read2_b64 v[4:7], v12 offset0:64 offset1:96
	ds_read2_b64 v[8:11], v12 offset0:128 offset1:160
	ds_read2_b64 v[12:15], v12 offset0:192 offset1:224
	s_waitcnt lgkmcnt(3)
	v_fma_f32 v16, 0, v0, v1
	v_pk_mul_f32 v[0:1], v[0:1], v[2:3]
	v_fma_f32 v2, v2, v16, v3
	s_waitcnt lgkmcnt(2)
	v_fma_f32 v2, v4, v2, v5
	v_fma_f32 v2, v6, v2, v7
	s_waitcnt lgkmcnt(1)
	v_fma_f32 v3, v8, v2, v9
	v_mov_b32_e32 v2, v0
	v_mov_b32_e32 v16, v4
	v_mov_b32_e32 v17, v10
	v_pk_mul_f32 v[0:1], v[0:1], v[4:5]
	v_pk_fma_f32 v[2:3], v[2:3], v[16:17], v[10:11]
	v_pk_mul_f32 v[0:1], v[0:1], v[6:7]
	s_waitcnt lgkmcnt(0)
	v_mov_b32_e32 v9, v12
	v_mov_b32_e32 v1, v3
	v_pk_mul_f32 v[2:3], v[0:1], v[8:9]
	v_pk_fma_f32 v[0:1], v[0:1], v[8:9], v[12:13]
	v_pk_mul_f32 v[2:3], v[2:3], v[10:11]
	v_mov_b32_e32 v4, v12
	v_mov_b32_e32 v0, v2
	v_mov_b32_e32 v5, v14
	v_pk_mul_f32 v[2:3], v[2:3], v[12:13]
	v_pk_fma_f32 v[0:1], v[0:1], v[4:5], v[14:15]
	v_pk_mul_f32 v[2:3], v[2:3], v[14:15]
	v_add_u32_e32 v0, 64, v92
	v_mov_b32_e32 v3, v1
	v_ashrrev_i32_e32 v1, 31, v0
	v_lshl_add_u64 v[0:1], v[0:1], 3, s[24:25]
	global_store_dwordx2 v[0:1], v[2:3], off
.LBB0_359:
	s_or_b64 exec, exec, s[8:9]
	s_setprio 1
	s_waitcnt lgkmcnt(0)
	v_mfma_f32_32x32x16_bf16 v[16:31], v[48:51], v[178:181], 0
	v_mfma_f32_32x32x16_bf16 v[32:47], v[48:51], v[186:189], 0
	v_mfma_f32_32x32x16_bf16 v[16:31], v[52:55], v[182:185], v[16:31]
	v_mfma_f32_32x32x16_bf16 v[32:47], v[52:55], v[190:193], v[32:47]
	v_mfma_f32_32x32x16_bf16 v[16:31], v[56:59], v[194:197], v[16:31]
	v_mfma_f32_32x32x16_bf16 v[32:47], v[56:59], v[206:209], v[32:47]
	v_mfma_f32_32x32x16_bf16 v[16:31], v[60:63], v[198:201], v[16:31]
	v_mfma_f32_32x32x16_bf16 v[32:47], v[60:63], v[202:205], v[32:47]
	v_mfma_f32_32x32x16_bf16 v[16:31], v[64:67], v[210:213], v[16:31]
	v_mfma_f32_32x32x16_bf16 v[32:47], v[64:67], v[222:225], v[32:47]
	v_mfma_f32_32x32x16_bf16 v[16:31], v[68:71], v[214:217], v[16:31]
	v_mfma_f32_32x32x16_bf16 v[32:47], v[68:71], v[218:221], v[32:47]
	v_mfma_f32_32x32x16_bf16 v[16:31], v[72:75], v[226:229], v[16:31]
	v_mfma_f32_32x32x16_bf16 v[32:47], v[72:75], v[238:241], v[32:47]
	v_mfma_f32_32x32x16_bf16 v[16:31], v[76:79], v[230:233], v[16:31]
	v_mfma_f32_32x32x16_bf16 v[32:47], v[76:79], v[234:237], v[32:47]
	v_mfma_f32_32x32x16_bf16 v[0:15], v[72:75], v[80:83], 0
	v_mfma_f32_32x32x16_bf16 v[0:15], v[76:79], v[84:87], v[0:15]
	s_setprio 0
	s_waitcnt vmcnt(16)
	ds_read_b32 v251, v167 offset:384
	v_mul_f32_e32 v49, 0xbfb8aa3b, v173
	v_mul_f32_e32 v48, 0xbfb8aa3b, v174
	s_nop 0
	v_fmamk_f32 v18, v18, 0xbfb8aa3b, v49
	v_fmamk_f32 v19, v19, 0xbfb8aa3b, v49
	v_fmamk_f32 v16, v16, 0xbfb8aa3b, v49
	v_fmamk_f32 v32, v32, 0xbfb8aa3b, v48
	v_fmamk_f32 v17, v17, 0xbfb8aa3b, v49
	v_exp_f32_e32 v18, v18
	v_fmamk_f32 v33, v33, 0xbfb8aa3b, v48
	v_exp_f32_e32 v59, v19
	v_exp_f32_e32 v50, v16
	v_exp_f32_e32 v32, v32
	v_exp_f32_e32 v51, v17
	v_exp_f32_e32 v33, v33
	v_add_f32_e32 v60, 1.0, v18
	v_add_f32_e32 v32, 1.0, v32
	v_add_f32_e32 v50, 1.0, v50
	v_add_f32_e32 v33, 1.0, v33
	v_rcp_f32_e32 v62, v32
	v_rcp_f32_e32 v61, v50
	v_rcp_f32_e32 v64, v33
	v_add_f32_e32 v51, 1.0, v51
	v_rcp_f32_e32 v63, v51
	v_fmamk_f32 v34, v34, 0xbfb8aa3b, v48
	v_exp_f32_e32 v34, v34
	v_fmamk_f32 v36, v36, 0xbfb8aa3b, v48
	v_add_f32_e32 v34, 1.0, v34
	v_exp_f32_e32 v36, v36
	s_nop 1
	s_nop 1
	s_waitcnt lgkmcnt(0)
	v_mul_f32_e32 v33, 0x3fb8aa3b, v251
	v_mul_f32_e32 v16, v61, v33
	v_exp_f32_e32 v32, v16
	v_rcp_f32_e32 v16, v60
	v_mul_f32_e32 v17, v63, v33
	v_fma_f32 v18, -v32, v32, 1.0
	v_sqrt_f32_e32 v18, v18
	v_mul_f32_e32 v16, v16, v33
	v_exp_f32_e32 v50, v17
	v_mul_f32_e32 v18, v62, v18
	v_mul_f32_e32 v18, v0, v18
	v_exp_f32_e32 v0, v16
	v_add_f32_e32 v16, 1.0, v59
	v_rcp_f32_e32 v16, v16
	v_fma_f32 v19, -v50, v50, 1.0
	v_sqrt_f32_e32 v19, v19
	v_rcp_f32_e32 v17, v34
	v_mul_f32_e32 v16, v16, v33
	v_exp_f32_e32 v51, v16
	v_fmamk_f32 v16, v20, 0xbfb8aa3b, v49
	v_mul_f32_e32 v34, v64, v19
	v_fmamk_f32 v19, v35, 0xbfb8aa3b, v48
	v_exp_f32_e32 v16, v16
	v_exp_f32_e32 v19, v19
	v_fma_f32 v20, -v51, v51, 1.0
	v_add_f32_e32 v16, 1.0, v16
	v_rcp_f32_e32 v16, v16
	v_add_f32_e32 v19, 1.0, v19
	v_rcp_f32_e32 v19, v19
	v_sqrt_f32_e32 v20, v20
	v_mul_f32_e32 v16, v16, v33
	v_fma_f32 v35, -v0, v0, 1.0
	v_mul_f32_e32 v52, v19, v20
	v_exp_f32_e32 v20, v16
	v_fmamk_f32 v16, v21, 0xbfb8aa3b, v49
	v_exp_f32_e32 v16, v16
	v_sqrt_f32_e32 v35, v35
	v_fma_f32 v19, -v20, v20, 1.0
	v_fmamk_f32 v21, v37, 0xbfb8aa3b, v48
	v_add_f32_e32 v16, 1.0, v16
	v_rcp_f32_e32 v16, v16
	v_mul_f32_e32 v35, v17, v35
	v_add_f32_e32 v17, 1.0, v36
	v_rcp_f32_e32 v17, v17
	v_mul_f32_e32 v16, v16, v33
	v_exp_f32_e32 v36, v16
	v_fmamk_f32 v16, v22, 0xbfb8aa3b, v49
	v_exp_f32_e32 v16, v16
	v_sqrt_f32_e32 v19, v19
	v_exp_f32_e32 v21, v21
	v_add_f32_e32 v16, 1.0, v16
	v_rcp_f32_e32 v16, v16
	v_mul_f32_e32 v17, v17, v19
	v_mul_f32_e32 v19, v4, v17
	v_add_f32_e32 v4, 1.0, v21
	v_fmamk_f32 v21, v38, 0xbfb8aa3b, v48
	v_mul_f32_e32 v16, v16, v33
	v_fma_f32 v17, -v36, v36, 1.0
	v_exp_f32_e32 v21, v21
	v_rcp_f32_e32 v4, v4
	v_sqrt_f32_e32 v17, v17
	v_exp_f32_e32 v37, v16
	v_add_f32_e32 v16, 1.0, v21
	v_fmamk_f32 v21, v23, 0xbfb8aa3b, v49
	v_mul_f32_e32 v4, v4, v17
	v_fma_f32 v17, -v37, v37, 1.0
	v_rcp_f32_e32 v16, v16
	v_sqrt_f32_e32 v17, v17
	v_exp_f32_e32 v21, v21
	v_fmamk_f32 v22, v39, 0xbfb8aa3b, v48
	v_mul_f32_e32 v23, v16, v17
	v_add_f32_e32 v16, 1.0, v21
	v_rcp_f32_e32 v16, v16
	v_fmamk_f32 v21, v24, 0xbfb8aa3b, v49
	v_exp_f32_e32 v21, v21
	v_mul_f32_e32 v16, v16, v33
	v_exp_f32_e32 v24, v16
	v_add_f32_e32 v16, 1.0, v21
	v_rcp_f32_e32 v16, v16
	v_exp_f32_e32 v22, v22
	v_fmamk_f32 v21, v40, 0xbfb8aa3b, v48
	v_mul_f32_e32 v16, v16, v33
	v_add_f32_e32 v17, 1.0, v22
	v_fma_f32 v22, -v24, v24, 1.0
	v_sqrt_f32_e32 v38, v22
	v_exp_f32_e32 v22, v16
	v_fmamk_f32 v16, v25, 0xbfb8aa3b, v49
	v_exp_f32_e32 v16, v16
	v_exp_f32_e32 v21, v21
	v_fmamk_f32 v39, v41, 0xbfb8aa3b, v48
	v_fma_f32 v25, -v22, v22, 1.0
	v_add_f32_e32 v16, 1.0, v16
	v_rcp_f32_e32 v16, v16
	v_add_f32_e32 v21, 1.0, v21
	v_rcp_f32_e32 v17, v17
	v_rcp_f32_e32 v21, v21
	v_sqrt_f32_e32 v25, v25
	v_exp_f32_e32 v39, v39
	v_mul_f32_e32 v16, v16, v33
	v_mul_f32_e32 v38, v17, v38
	v_mul_f32_e32 v17, v21, v25
	v_add_f32_e32 v21, 1.0, v39
	v_exp_f32_e32 v39, v16
	v_fmamk_f32 v16, v26, 0xbfb8aa3b, v49
	v_exp_f32_e32 v16, v16
	v_rcp_f32_e32 v25, v21
	v_fma_f32 v21, -v39, v39, 1.0
	v_sqrt_f32_e32 v26, v21
	v_add_f32_e32 v16, 1.0, v16
	v_fmamk_f32 v21, v42, 0xbfb8aa3b, v48
	v_rcp_f32_e32 v16, v16
	v_exp_f32_e32 v40, v21
	v_mul_f32_e32 v21, v8, v17
	v_mul_f32_e32 v16, v16, v33
	v_add_f32_e32 v17, 1.0, v40
	v_exp_f32_e32 v40, v16
	v_fmamk_f32 v16, v27, 0xbfb8aa3b, v49
	v_exp_f32_e32 v16, v16
	v_mul_f32_e32 v8, v25, v26
	v_fma_f32 v25, -v40, v40, 1.0
	v_fmamk_f32 v26, v43, 0xbfb8aa3b, v48
	v_add_f32_e32 v16, 1.0, v16
	v_rcp_f32_e32 v16, v16
	v_rcp_f32_e32 v17, v17
	v_sqrt_f32_e32 v25, v25
	v_mul_f32_e32 v16, v16, v33
	v_exp_f32_e32 v26, v26
	v_exp_f32_e32 v41, v16
	v_mul_f32_e32 v53, v17, v25
	v_fmamk_f32 v25, v28, 0xbfb8aa3b, v49
	v_add_f32_e32 v16, 1.0, v26
	v_fmamk_f32 v26, v44, 0xbfb8aa3b, v48
	v_fma_f32 v17, -v41, v41, 1.0
	v_exp_f32_e32 v25, v25
	v_rcp_f32_e32 v16, v16
	v_sqrt_f32_e32 v17, v17
	v_exp_f32_e32 v26, v26
	v_add_f32_e32 v25, 1.0, v25
	v_rcp_f32_e32 v25, v25
	v_mul_f32_e32 v54, v16, v17
	v_add_f32_e32 v16, 1.0, v26
	v_fmamk_f32 v26, v45, 0xbfb8aa3b, v48
	v_exp_f32_e32 v26, v26
	v_rcp_f32_e32 v17, v16
	v_mul_f32_e32 v16, v25, v33
	v_fmamk_f32 v25, v29, 0xbfb8aa3b, v49
	v_exp_f32_e32 v25, v25
	v_add_f32_e32 v26, 1.0, v26
	v_rcp_f32_e32 v42, v26
	v_fmamk_f32 v26, v30, 0xbfb8aa3b, v49
	v_exp_f32_e32 v26, v26
	v_add_f32_e32 v25, 1.0, v25
	v_rcp_f32_e32 v25, v25
	v_fmamk_f32 v27, v46, 0xbfb8aa3b, v48
	v_exp_f32_e32 v27, v27
	v_add_f32_e32 v26, 1.0, v26
	v_rcp_f32_e32 v26, v26
	v_mul_f32_e32 v25, v25, v33
	v_exp_f32_e32 v43, v25
	v_add_f32_e32 v25, 1.0, v27
	v_rcp_f32_e32 v44, v25
	v_mul_f32_e32 v25, v26, v33
	v_fmamk_f32 v26, v31, 0xbfb8aa3b, v49
	v_exp_f32_e32 v26, v26
	v_fmamk_f32 v27, v47, 0xbfb8aa3b, v48
	v_exp_f32_e32 v27, v27
	v_add_f32_e32 v26, 1.0, v26
	v_rcp_f32_e32 v26, v26
	v_exp_f32_e32 v16, v16
	v_fmac_f32_e32 v18, 0, v32
	v_exp_f32_e32 v45, v25
	v_add_f32_e32 v25, 1.0, v27
	v_mul_f32_e32 v31, v50, v18
	v_rcp_f32_e32 v46, v25
	v_mul_f32_e32 v25, v26, v33
	v_fmac_f32_e32 v31, v1, v34
	v_mul_f32_e32 v33, v32, v50
	v_fmac_f32_e32 v19, 0, v20
	v_mul_f32_e32 v30, v0, v31
	v_mul_f32_e32 v34, v0, v33
	v_mul_f32_e32 v28, v36, v19
	v_fma_f32 v0, -v16, v16, 1.0
	v_fmac_f32_e32 v28, v5, v4
	v_sqrt_f32_e32 v1, v0
	v_mul_f32_e32 v27, v37, v28
	v_fmac_f32_e32 v30, v2, v35
	v_fmac_f32_e32 v27, v6, v23
	v_fma_f32 v2, -v43, v43, 1.0
	v_mul_f32_e32 v26, v24, v27
	v_mov_b32_e32 v0, v89
	v_sqrt_f32_e32 v2, v2
	v_fmac_f32_e32 v26, v7, v38
	v_pk_mul_f32 v[6:7], v[16:17], v[0:1]
	v_mul_f32_e32 v29, v51, v30
	v_fmac_f32_e32 v6, v12, v7
	v_fmac_f32_e32 v29, v3, v52
	v_mov_b32_e32 v3, v6
	v_pk_mul_f32 v[4:5], v[42:43], v[2:3]
	v_fma_f32 v0, -v45, v45, 1.0
	v_exp_f32_e32 v47, v25
	v_fmac_f32_e32 v5, v13, v4
	v_sqrt_f32_e32 v4, v0
	v_fmac_f32_e32 v21, 0, v22
	v_mul_f32_e32 v25, v39, v21
	v_mul_f32_e32 v36, v20, v36
	v_fmac_f32_e32 v25, v9, v8
	v_pk_mul_f32 v[8:9], v[44:45], v[4:5]
	v_fma_f32 v0, -v47, v47, 1.0
	v_mul_f32_e32 v37, v37, v36
	v_fmac_f32_e32 v9, v14, v8
	v_sqrt_f32_e32 v8, v0
	ds_bpermute_b32 v0, v140, v29
	v_mul_f32_e32 v38, v24, v37
	v_mul_f32_e32 v24, v40, v25
	v_mul_f32_e32 v35, v51, v34
	v_fmac_f32_e32 v24, v10, v53
	v_mul_f32_e32 v23, v41, v24
	ds_bpermute_b32 v13, v140, v35
	v_fmac_f32_e32 v23, v11, v54
	v_pk_mul_f32 v[10:11], v[46:47], v[8:9]
	s_waitcnt lgkmcnt(1)
	v_cndmask_b32_e64 v14, v29, v0, s[0:1]
	v_fmac_f32_e32 v11, v15, v10
	v_cndmask_b32_e64 v10, v0, v29, s[0:1]
	ds_bpermute_b32 v0, v140, v38
	ds_bpermute_b32 v3, v140, v26
	v_mul_f32_e32 v39, v22, v39
	v_mul_f32_e32 v40, v40, v39
	s_waitcnt lgkmcnt(2)
	v_cndmask_b32_e64 v1, v13, v35, s[0:1]
	v_mul_f32_e32 v12, v41, v40
	v_mul_f32_e32 v7, v16, v43
	v_cndmask_b32_e64 v2, v35, v13, s[0:1]
	v_fmac_f32_e32 v10, 0, v1
	v_mul_f32_e32 v4, v45, v7
	v_mul_f32_e32 v15, v35, v13
	v_fmac_f32_e32 v14, v2, v10
	s_waitcnt lgkmcnt(1)
	v_cndmask_b32_e64 v1, v0, v38, s[0:1]
	s_waitcnt lgkmcnt(0)
	v_cndmask_b32_e64 v17, v3, v26, s[0:1]
	v_cndmask_b32_e64 v41, v26, v3, s[0:1]
	ds_bpermute_b32 v2, v140, v12
	ds_bpermute_b32 v3, v140, v23
	v_mul_f32_e32 v8, v47, v4
	v_cndmask_b32_e64 v0, v38, v0, s[0:1]
	v_mul_f32_e32 v42, v15, v1
	v_fmac_f32_e32 v17, v1, v14
	v_mul_f32_e32 v43, v0, v42
	v_fmac_f32_e32 v41, v0, v17
	ds_bpermute_b32 v1, v140, v8
	ds_bpermute_b32 v0, v140, v11
	s_waitcnt lgkmcnt(3)
	v_cndmask_b32_e64 v47, v2, v12, s[0:1]
	s_waitcnt lgkmcnt(2)
	v_cndmask_b32_e64 v44, v3, v23, s[0:1]
	v_cndmask_b32_e64 v2, v12, v2, s[0:1]
	v_cndmask_b32_e64 v45, v23, v3, s[0:1]
	v_mul_f32_e32 v46, v47, v43
	v_fmac_f32_e32 v44, v47, v41
	v_mul_f32_e32 v47, v2, v46
	v_fmac_f32_e32 v45, v2, v44
	s_waitcnt lgkmcnt(1)
	v_cndmask_b32_e64 v2, v1, v8, s[0:1]
	s_waitcnt lgkmcnt(0)
	v_cndmask_b32_e64 v48, v0, v11, s[0:1]
	v_mul_f32_e32 v49, v2, v47
	v_fmac_f32_e32 v48, v2, v45
	s_and_saveexec_b64 s[8:9], s[0:1]
	v_mul_f32_e32 v3, v48, v1
	v_mul_f32_e32 v2, v49, v1
	v_add_f32_e32 v3, v3, v0
	ds_write_b64 v139, v[2:3] offset:6144
	s_or_b64 exec, exec, s[8:9]
	s_and_b64 vcc, exec, s[6:7]
	s_waitcnt lgkmcnt(0)
	s_barrier
	s_cbranch_vccnz .LBB0_366
	s_cmp_lt_u32 s62, 8
	s_cbranch_scc1 .LBB0_367
	s_and_b32 s6, s62, 0x7ffffff8
	v_add3_u32 v50, v141, v138, s88
	v_mov_b32_e32 v0, 1.0
	v_mov_b32_e32 v3, 0
	s_mov_b32 s7, 0
